# P4 stores (YSSM, YMIX retention half) sc1, on top of v102
# baseline (speedup 1.0000x reference)
.LBB0_571:
	v_mul_f32_e32 v156, 0x3d372713, v124
	v_mul_f32_e32 v156, v124, v156
	v_fma_f32 v156, v124, v156, v124
	v_mul_f32_e32 v156, 0x3fcc422a, v156
	v_mul_f32_e32 v156, 0xbfb8aa3b, v156
	v_exp_f32_e32 v158, v156
	v_mul_f32_e32 v156, 0x3d372713, v120
	v_mul_f32_e32 v156, v120, v156
	v_fma_f32 v156, v120, v156, v120
	v_mul_f32_e32 v156, 0x3fcc422a, v156
	v_mul_f32_e32 v156, 0xbfb8aa3b, v156
	v_exp_f32_e32 v159, v156
	v_lshl_add_u32 v142, s50, 8, v148
	v_ashrrev_i32_e32 v143, 31, v142
	v_lshlrev_b64 v[156:157], 15, v[142:143]
	v_add_f32_e32 v143, 1.0, v158
	v_rcp_f32_e32 v158, v143
	v_add_f32_e32 v143, 1.0, v159
	v_mul_f32_e32 v159, 0x3d372713, v125
	v_mul_f32_e32 v159, v125, v159
	v_mul_f32_e32 v160, 0x3d372713, v121
	v_fma_f32 v159, v125, v159, v125
	v_mul_f32_e32 v160, v121, v160
	v_mul_f32_e32 v159, 0x3fcc422a, v159
	v_fma_f32 v160, v121, v160, v121
	v_mul_f32_e32 v159, 0xbfb8aa3b, v159
	v_mul_f32_e32 v160, 0x3fcc422a, v160
	v_exp_f32_e32 v159, v159
	v_mul_f32_e32 v160, 0xbfb8aa3b, v160
	v_exp_f32_e32 v161, v160
	v_rcp_f32_e32 v160, v143
	v_add_f32_e32 v143, 1.0, v159
	v_rcp_f32_e32 v159, v143
	v_add_f32_e32 v143, 1.0, v161
	v_mul_f32_e32 v161, 0x3d372713, v126
	v_mul_f32_e32 v161, v126, v161
	v_fma_f32 v161, v126, v161, v126
	v_mul_f32_e32 v161, 0x3fcc422a, v161
	v_mul_f32_e32 v161, 0xbfb8aa3b, v161
	v_exp_f32_e32 v162, v161
	v_mul_f32_e32 v161, 0x3d372713, v122
	v_mul_f32_e32 v161, v122, v161
	v_fma_f32 v161, v122, v161, v122
	v_mul_f32_e32 v161, 0x3fcc422a, v161
	v_mul_f32_e32 v161, 0xbfb8aa3b, v161
	v_exp_f32_e32 v163, v161
	v_rcp_f32_e32 v161, v143
	v_add_f32_e32 v143, 1.0, v162
	v_rcp_f32_e32 v162, v143
	v_add_f32_e32 v143, 1.0, v163
	v_mul_f32_e32 v163, 0x3d372713, v127
	v_mul_f32_e32 v163, v127, v163
	v_mul_f32_e32 v164, 0x3d372713, v123
	v_fma_f32 v163, v127, v163, v127
	v_mul_f32_e32 v164, v123, v164
	v_mul_f32_e32 v163, 0x3fcc422a, v163
	v_fma_f32 v164, v123, v164, v123
	v_mul_f32_e32 v163, 0xbfb8aa3b, v163
	v_mul_f32_e32 v164, 0x3fcc422a, v164
	v_exp_f32_e32 v163, v163
	v_mul_f32_e32 v164, 0xbfb8aa3b, v164
	v_exp_f32_e32 v165, v164
	v_rcp_f32_e32 v164, v143
	v_add_f32_e32 v143, 1.0, v163
	v_rcp_f32_e32 v163, v143
	v_add_f32_e32 v143, 1.0, v165
	v_rcp_f32_e32 v165, v143
	v_lshl_or_b32 v155, s49, 8, v149
	v_pk_mul_f32 v[124:125], v[124:125], v[158:159]
	v_ashrrev_i32_e32 v158, 4, v155
	s_lshl_b32 s20, s33, 4
	v_pk_mul_f32 v[120:121], v[120:121], v[160:161]
	v_pk_mul_f32 v[126:127], v[126:127], v[162:163]
	v_pk_mul_f32 v[122:123], v[122:123], v[164:165]
	v_ashrrev_i32_e32 v159, 31, v158
	s_ashr_i32 s21, s20, 31
	v_cvt_pk_bf16_f32 v124, v124, v125
	v_cvt_pk_bf16_f32 v125, v126, v127
	v_cvt_pk_bf16_f32 v126, v120, v121
	v_cvt_pk_bf16_f32 v127, v122, v123
	v_lshl_add_u64 v[120:121], s[84:85], 0, v[156:157]
	v_lshlrev_b64 v[122:123], 10, v[158:159]
	v_lshl_add_u64 v[156:157], v[120:121], 0, v[122:123]
	s_lshl_b64 s[20:21], s[20:21], 1
	v_lshl_add_u64 v[156:157], v[156:157], 0, s[20:21]
	v_lshl_add_u64 v[156:157], v[156:157], 0, v[136:137]
	global_store_dwordx4 v[156:157], v[124:127], off sc1
	v_mul_f32_e32 v143, 0x3d372713, v116
	v_mul_f32_e32 v143, v116, v143
	v_mul_f32_e32 v126, 0x3d372713, v117
	v_mul_f32_e32 v126, v117, v126
	v_fma_f32 v126, v117, v126, v117
	v_fma_f32 v143, v116, v143, v116
	v_mul_f32_e32 v126, 0x3fcc422a, v126
	v_mul_f32_e32 v143, 0x3fcc422a, v143
	v_mul_f32_e32 v155, 0x3d372713, v112
	v_mul_f32_e32 v126, 0xbfb8aa3b, v126
	v_mul_f32_e32 v143, 0xbfb8aa3b, v143
	v_mul_f32_e32 v155, v112, v155
	v_exp_f32_e32 v127, v126
	v_mul_f32_e32 v126, 0x3d372713, v113
	v_exp_f32_e32 v143, v143
	v_fma_f32 v155, v112, v155, v112
	v_mul_f32_e32 v126, v113, v126
	v_mul_f32_e32 v155, 0x3fcc422a, v155
	v_fma_f32 v126, v113, v126, v113
	v_mul_f32_e32 v155, 0xbfb8aa3b, v155
	v_mul_f32_e32 v126, 0x3fcc422a, v126
	v_exp_f32_e32 v155, v155
	v_mul_f32_e32 v126, 0xbfb8aa3b, v126
	v_add_f32_e32 v124, 1.0, v143
	v_exp_f32_e32 v143, v126
	v_add_f32_e32 v125, 1.0, v155
	v_rcp_f32_e32 v126, v125
	v_add_f32_e32 v125, 1.0, v127
	v_add_f32_e32 v127, 1.0, v143
	v_mul_f32_e32 v143, 0x3d372713, v118
	v_mul_f32_e32 v143, v118, v143
	v_mul_f32_e32 v155, 0x3d372713, v114
	v_fma_f32 v143, v118, v143, v118
	v_mul_f32_e32 v155, v114, v155
	v_mul_f32_e32 v143, 0x3fcc422a, v143
	v_fma_f32 v155, v114, v155, v114
	v_mul_f32_e32 v143, 0xbfb8aa3b, v143
	v_mul_f32_e32 v155, 0x3fcc422a, v155
	v_exp_f32_e32 v143, v143
	v_mul_f32_e32 v155, 0xbfb8aa3b, v155
	v_exp_f32_e32 v155, v155
	v_mul_f32_e32 v157, 0x3d372713, v115
	v_add_f32_e32 v143, 1.0, v143
	v_rcp_f32_e32 v156, v143
	v_add_f32_e32 v143, 1.0, v155
	v_mul_f32_e32 v155, 0x3d372713, v119
	v_mul_f32_e32 v155, v119, v155
	v_fma_f32 v155, v119, v155, v119
	v_mul_f32_e32 v157, v115, v157
	v_mul_f32_e32 v155, 0x3fcc422a, v155
	v_fma_f32 v157, v115, v157, v115
	v_mul_f32_e32 v155, 0xbfb8aa3b, v155
	v_mul_f32_e32 v157, 0x3fcc422a, v157
	v_exp_f32_e32 v155, v155
	v_mul_f32_e32 v157, 0xbfb8aa3b, v157
	v_exp_f32_e32 v159, v157
	v_rcp_f32_e32 v127, v127
	v_rcp_f32_e32 v160, v143
	v_add_f32_e32 v143, 1.0, v155
	v_rcp_f32_e32 v124, v124
	v_rcp_f32_e32 v125, v125
	v_rcp_f32_e32 v157, v143
	v_add_f32_e32 v143, 1.0, v159
	v_rcp_f32_e32 v161, v143
	v_pk_mul_f32 v[112:113], v[112:113], v[126:127]
	v_or_b32_e32 v126, 8, v158
	v_pk_mul_f32 v[116:117], v[116:117], v[124:125]
	v_ashrrev_i32_e32 v127, 31, v126
	v_pk_mul_f32 v[118:119], v[118:119], v[156:157]
	v_pk_mul_f32 v[124:125], v[114:115], v[160:161]
	v_cvt_pk_bf16_f32 v114, v116, v117
	v_cvt_pk_bf16_f32 v116, v112, v113
	v_lshlrev_b64 v[112:113], 10, v[126:127]
	v_cvt_pk_bf16_f32 v115, v118, v119
	v_lshl_add_u64 v[118:119], v[120:121], 0, v[112:113]
	v_lshl_add_u64 v[118:119], v[118:119], 0, s[20:21]
	v_cvt_pk_bf16_f32 v117, v124, v125
	v_lshl_add_u64 v[118:119], v[118:119], 0, v[136:137]
	global_store_dwordx4 v[118:119], v[114:117], off sc1
	v_mul_f32_e32 v118, 0x3d372713, v109
	v_mul_f32_e32 v118, v109, v118
	v_fma_f32 v118, v109, v118, v109
	v_mul_f32_e32 v118, 0x3fcc422a, v118
	v_mul_f32_e32 v117, 0x3d372713, v104
	v_mul_f32_e32 v118, 0xbfb8aa3b, v118
	v_mul_f32_e32 v117, v104, v117
	v_exp_f32_e32 v119, v118
	v_mul_f32_e32 v118, 0x3d372713, v105
	v_fma_f32 v117, v104, v117, v104
	v_mul_f32_e32 v118, v105, v118
	v_mul_f32_e32 v117, 0x3fcc422a, v117
	v_fma_f32 v118, v105, v118, v105
	v_mul_f32_e32 v117, 0xbfb8aa3b, v117
	v_mul_f32_e32 v118, 0x3fcc422a, v118
	v_exp_f32_e32 v117, v117
	v_mul_f32_e32 v118, 0xbfb8aa3b, v118
	v_exp_f32_e32 v124, v118
	v_mul_f32_e32 v126, 0x3d372713, v111
	v_mul_f32_e32 v126, v111, v126
	v_mul_f32_e32 v116, 0x3d372713, v108
	v_add_f32_e32 v117, 1.0, v117
	v_mul_f32_e32 v125, 0x3d372713, v106
	v_fma_f32 v126, v111, v126, v111
	v_mul_f32_e32 v116, v108, v116
	v_rcp_f32_e32 v118, v117
	v_add_f32_e32 v117, 1.0, v119
	v_add_f32_e32 v119, 1.0, v124
	v_mul_f32_e32 v124, 0x3d372713, v110
	v_mul_f32_e32 v125, v106, v125
	v_mul_f32_e32 v126, 0x3fcc422a, v126
	v_fma_f32 v116, v108, v116, v108
	v_mul_f32_e32 v124, v110, v124
	v_fma_f32 v125, v106, v125, v106
	v_mul_f32_e32 v126, 0xbfb8aa3b, v126
	v_mul_f32_e32 v116, 0x3fcc422a, v116
	v_fma_f32 v124, v110, v124, v110
	v_mul_f32_e32 v125, 0x3fcc422a, v125
	v_exp_f32_e32 v127, v126
	v_mul_f32_e32 v126, 0x3d372713, v107
	v_mul_f32_e32 v116, 0xbfb8aa3b, v116
	v_mul_f32_e32 v124, 0x3fcc422a, v124
	v_mul_f32_e32 v125, 0xbfb8aa3b, v125
	v_mul_f32_e32 v126, v107, v126
	v_exp_f32_e32 v116, v116
	v_mul_f32_e32 v124, 0xbfb8aa3b, v124
	v_exp_f32_e32 v125, v125
	v_fma_f32 v126, v107, v126, v107
	v_exp_f32_e32 v124, v124
	v_mul_f32_e32 v126, 0x3fcc422a, v126
	v_mul_f32_e32 v126, 0xbfb8aa3b, v126
	v_exp_f32_e32 v143, v126
	v_add_f32_e32 v116, 1.0, v116
	v_add_f32_e32 v125, 1.0, v125
	v_rcp_f32_e32 v116, v116
	v_rcp_f32_e32 v117, v117
	v_add_f32_e32 v124, 1.0, v124
	v_rcp_f32_e32 v126, v125
	v_add_f32_e32 v125, 1.0, v127
	v_rcp_f32_e32 v119, v119
	v_rcp_f32_e32 v124, v124
	v_rcp_f32_e32 v125, v125
	v_or_b32_e32 v114, 16, v142
	v_add_f32_e32 v127, 1.0, v143
	v_ashrrev_i32_e32 v115, 31, v114
	v_rcp_f32_e32 v127, v127
	v_lshlrev_b64 v[114:115], 15, v[114:115]
	v_pk_mul_f32 v[108:109], v[108:109], v[116:117]
	v_pk_mul_f32 v[116:117], v[104:105], v[118:119]
	v_pk_mul_f32 v[110:111], v[110:111], v[124:125]
	v_cvt_pk_bf16_f32 v104, v108, v109
	v_lshl_add_u64 v[108:109], s[84:85], 0, v[114:115]
	v_cvt_pk_bf16_f32 v105, v110, v111
	v_lshl_add_u64 v[110:111], v[108:109], 0, v[122:123]
	v_pk_mul_f32 v[118:119], v[106:107], v[126:127]
	v_lshl_add_u64 v[110:111], v[110:111], 0, s[20:21]
	v_cvt_pk_bf16_f32 v106, v116, v117
	v_cvt_pk_bf16_f32 v107, v118, v119
	v_lshl_add_u64 v[110:111], v[110:111], 0, v[136:137]
	v_mul_f32_e32 v114, 0x3d372713, v100
	global_store_dwordx4 v[110:111], v[104:107], off sc1
	v_mul_f32_e32 v114, v100, v114
	v_fma_f32 v114, v100, v114, v100
	v_mul_f32_e32 v106, 0x3d372713, v101
	v_mul_f32_e32 v106, v101, v106
	v_fma_f32 v106, v101, v106, v101
	v_mul_f32_e32 v114, 0x3fcc422a, v114
	v_mul_f32_e32 v106, 0x3fcc422a, v106
	v_mul_f32_e32 v114, 0xbfb8aa3b, v114
	v_mul_f32_e32 v115, 0x3d372713, v96
	v_mul_f32_e32 v106, 0xbfb8aa3b, v106
	v_exp_f32_e32 v114, v114
	v_mul_f32_e32 v115, v96, v115
	v_exp_f32_e32 v107, v106
	v_mul_f32_e32 v106, 0x3d372713, v97
	v_fma_f32 v115, v96, v115, v96
	v_mul_f32_e32 v106, v97, v106
	v_mul_f32_e32 v115, 0x3fcc422a, v115
	v_fma_f32 v106, v97, v106, v97
	v_mul_f32_e32 v115, 0xbfb8aa3b, v115
	v_mul_f32_e32 v106, 0x3fcc422a, v106
	v_exp_f32_e32 v115, v115
	v_add_f32_e32 v104, 1.0, v114
	v_mul_f32_e32 v106, 0xbfb8aa3b, v106
	v_mul_f32_e32 v114, 0x3d372713, v103
	v_exp_f32_e32 v110, v106
	v_mul_f32_e32 v114, v103, v114
	v_fma_f32 v114, v103, v114, v103
	v_mul_f32_e32 v114, 0x3fcc422a, v114
	v_add_f32_e32 v105, 1.0, v115
	v_mul_f32_e32 v111, 0x3d372713, v98
	v_mul_f32_e32 v114, 0xbfb8aa3b, v114
	v_rcp_f32_e32 v106, v105
	v_add_f32_e32 v105, 1.0, v107
	v_add_f32_e32 v107, 1.0, v110
	v_mul_f32_e32 v110, 0x3d372713, v102
	v_mul_f32_e32 v111, v98, v111
	v_exp_f32_e32 v115, v114
	v_mul_f32_e32 v114, 0x3d372713, v99
	v_mul_f32_e32 v110, v102, v110
	v_fma_f32 v111, v98, v111, v98
	v_mul_f32_e32 v114, v99, v114
	v_fma_f32 v110, v102, v110, v102
	v_mul_f32_e32 v111, 0x3fcc422a, v111
	v_fma_f32 v114, v99, v114, v99
	v_mul_f32_e32 v110, 0x3fcc422a, v110
	v_mul_f32_e32 v111, 0xbfb8aa3b, v111
	v_mul_f32_e32 v114, 0x3fcc422a, v114
	v_mul_f32_e32 v110, 0xbfb8aa3b, v110
	v_exp_f32_e32 v111, v111
	v_mul_f32_e32 v114, 0xbfb8aa3b, v114
	v_exp_f32_e32 v110, v110
	v_exp_f32_e32 v116, v114
	v_rcp_f32_e32 v104, v104
	v_rcp_f32_e32 v105, v105
	v_add_f32_e32 v111, 1.0, v111
	v_rcp_f32_e32 v107, v107
	v_add_f32_e32 v110, 1.0, v110
	v_rcp_f32_e32 v114, v111
	v_add_f32_e32 v111, 1.0, v115
	v_add_f32_e32 v115, 1.0, v116
	v_rcp_f32_e32 v110, v110
	v_rcp_f32_e32 v111, v111
	v_rcp_f32_e32 v115, v115
	v_pk_mul_f32 v[100:101], v[100:101], v[104:105]
	v_pk_mul_f32 v[104:105], v[96:97], v[106:107]
	v_cvt_pk_bf16_f32 v96, v100, v101
	v_lshl_add_u64 v[100:101], v[108:109], 0, v[112:113]
	v_pk_mul_f32 v[102:103], v[102:103], v[110:111]
	v_pk_mul_f32 v[106:107], v[98:99], v[114:115]
	v_lshl_add_u64 v[100:101], v[100:101], 0, s[20:21]
	v_cvt_pk_bf16_f32 v97, v102, v103
	v_cvt_pk_bf16_f32 v98, v104, v105
	v_cvt_pk_bf16_f32 v99, v106, v107
	v_lshl_add_u64 v[100:101], v[100:101], 0, v[136:137]
	global_store_dwordx4 v[100:101], v[96:99], off sc1
	v_mul_f32_e32 v100, 0x3d372713, v93
	v_mul_f32_e32 v100, v93, v100
	v_fma_f32 v100, v93, v100, v93
	v_mul_f32_e32 v100, 0x3fcc422a, v100
	v_mul_f32_e32 v99, 0x3d372713, v88
	v_mul_f32_e32 v100, 0xbfb8aa3b, v100
	v_mul_f32_e32 v99, v88, v99
	v_exp_f32_e32 v101, v100
	v_mul_f32_e32 v100, 0x3d372713, v89
	v_fma_f32 v99, v88, v99, v88
	v_mul_f32_e32 v100, v89, v100
	v_mul_f32_e32 v99, 0x3fcc422a, v99
	v_fma_f32 v100, v89, v100, v89
	v_mul_f32_e32 v99, 0xbfb8aa3b, v99
	v_mul_f32_e32 v100, 0x3fcc422a, v100
	v_exp_f32_e32 v99, v99
	v_mul_f32_e32 v100, 0xbfb8aa3b, v100
	v_exp_f32_e32 v102, v100
	v_mul_f32_e32 v104, 0x3d372713, v95
	v_mul_f32_e32 v104, v95, v104
	v_mul_f32_e32 v98, 0x3d372713, v92
	v_add_f32_e32 v99, 1.0, v99
	v_mul_f32_e32 v103, 0x3d372713, v90
	v_fma_f32 v104, v95, v104, v95
	v_mul_f32_e32 v98, v92, v98
	v_rcp_f32_e32 v100, v99
	v_add_f32_e32 v99, 1.0, v101
	v_add_f32_e32 v101, 1.0, v102
	v_mul_f32_e32 v102, 0x3d372713, v94
	v_mul_f32_e32 v103, v90, v103
	v_mul_f32_e32 v104, 0x3fcc422a, v104
	v_fma_f32 v98, v92, v98, v92
	v_mul_f32_e32 v102, v94, v102
	v_fma_f32 v103, v90, v103, v90
	v_mul_f32_e32 v104, 0xbfb8aa3b, v104
	v_mul_f32_e32 v98, 0x3fcc422a, v98
	v_fma_f32 v102, v94, v102, v94
	v_mul_f32_e32 v103, 0x3fcc422a, v103
	v_exp_f32_e32 v105, v104
	v_mul_f32_e32 v104, 0x3d372713, v91
	v_mul_f32_e32 v98, 0xbfb8aa3b, v98
	v_mul_f32_e32 v102, 0x3fcc422a, v102
	v_mul_f32_e32 v103, 0xbfb8aa3b, v103
	v_mul_f32_e32 v104, v91, v104
	v_exp_f32_e32 v98, v98
	v_mul_f32_e32 v102, 0xbfb8aa3b, v102
	v_exp_f32_e32 v103, v103
	v_fma_f32 v104, v91, v104, v91
	v_exp_f32_e32 v102, v102
	v_mul_f32_e32 v104, 0x3fcc422a, v104
	v_mul_f32_e32 v104, 0xbfb8aa3b, v104
	v_exp_f32_e32 v106, v104
	v_add_f32_e32 v98, 1.0, v98
	v_add_f32_e32 v103, 1.0, v103
	v_rcp_f32_e32 v98, v98
	v_rcp_f32_e32 v99, v99
	v_add_f32_e32 v102, 1.0, v102
	v_rcp_f32_e32 v104, v103
	v_add_f32_e32 v103, 1.0, v105
	v_rcp_f32_e32 v101, v101
	v_rcp_f32_e32 v102, v102
	v_rcp_f32_e32 v103, v103
	v_or_b32_e32 v96, 32, v142
	v_add_f32_e32 v105, 1.0, v106
	v_ashrrev_i32_e32 v97, 31, v96
	v_rcp_f32_e32 v105, v105
	v_lshlrev_b64 v[96:97], 15, v[96:97]
	v_pk_mul_f32 v[92:93], v[92:93], v[98:99]
	v_pk_mul_f32 v[98:99], v[88:89], v[100:101]
	v_pk_mul_f32 v[94:95], v[94:95], v[102:103]
	v_cvt_pk_bf16_f32 v88, v92, v93
	v_lshl_add_u64 v[92:93], s[84:85], 0, v[96:97]
	v_cvt_pk_bf16_f32 v89, v94, v95
	v_lshl_add_u64 v[94:95], v[92:93], 0, v[122:123]
	v_pk_mul_f32 v[100:101], v[90:91], v[104:105]
	v_lshl_add_u64 v[94:95], v[94:95], 0, s[20:21]
	v_cvt_pk_bf16_f32 v90, v98, v99
	v_cvt_pk_bf16_f32 v91, v100, v101
	v_lshl_add_u64 v[94:95], v[94:95], 0, v[136:137]
	v_mul_f32_e32 v96, 0x3d372713, v84
	global_store_dwordx4 v[94:95], v[88:91], off sc1
	v_mul_f32_e32 v96, v84, v96
	v_fma_f32 v96, v84, v96, v84
	v_mul_f32_e32 v90, 0x3d372713, v85
	v_mul_f32_e32 v90, v85, v90
	v_fma_f32 v90, v85, v90, v85
	v_mul_f32_e32 v96, 0x3fcc422a, v96
	v_mul_f32_e32 v90, 0x3fcc422a, v90
	v_mul_f32_e32 v96, 0xbfb8aa3b, v96
	v_mul_f32_e32 v97, 0x3d372713, v80
	v_mul_f32_e32 v90, 0xbfb8aa3b, v90
	v_exp_f32_e32 v96, v96
	v_mul_f32_e32 v97, v80, v97
	v_exp_f32_e32 v91, v90
	v_mul_f32_e32 v90, 0x3d372713, v81
	v_fma_f32 v97, v80, v97, v80
	v_mul_f32_e32 v90, v81, v90
	v_mul_f32_e32 v97, 0x3fcc422a, v97
	v_fma_f32 v90, v81, v90, v81
	v_mul_f32_e32 v97, 0xbfb8aa3b, v97
	v_mul_f32_e32 v90, 0x3fcc422a, v90
	v_exp_f32_e32 v97, v97
	v_add_f32_e32 v88, 1.0, v96
	v_mul_f32_e32 v90, 0xbfb8aa3b, v90
	v_mul_f32_e32 v96, 0x3d372713, v87
	v_exp_f32_e32 v94, v90
	v_mul_f32_e32 v96, v87, v96
	v_fma_f32 v96, v87, v96, v87
	v_mul_f32_e32 v96, 0x3fcc422a, v96
	v_add_f32_e32 v89, 1.0, v97
	v_mul_f32_e32 v95, 0x3d372713, v82
	v_mul_f32_e32 v96, 0xbfb8aa3b, v96
	v_rcp_f32_e32 v90, v89
	v_add_f32_e32 v89, 1.0, v91
	v_add_f32_e32 v91, 1.0, v94
	v_mul_f32_e32 v94, 0x3d372713, v86
	v_mul_f32_e32 v95, v82, v95
	v_exp_f32_e32 v97, v96
	v_mul_f32_e32 v96, 0x3d372713, v83
	v_mul_f32_e32 v94, v86, v94
	v_fma_f32 v95, v82, v95, v82
	v_mul_f32_e32 v96, v83, v96
	v_fma_f32 v94, v86, v94, v86
	v_mul_f32_e32 v95, 0x3fcc422a, v95
	v_fma_f32 v96, v83, v96, v83
	v_mul_f32_e32 v94, 0x3fcc422a, v94
	v_mul_f32_e32 v95, 0xbfb8aa3b, v95
	v_mul_f32_e32 v96, 0x3fcc422a, v96
	v_mul_f32_e32 v94, 0xbfb8aa3b, v94
	v_exp_f32_e32 v95, v95
	v_mul_f32_e32 v96, 0xbfb8aa3b, v96
	v_exp_f32_e32 v94, v94
	v_exp_f32_e32 v98, v96
	v_rcp_f32_e32 v88, v88
	v_rcp_f32_e32 v89, v89
	v_add_f32_e32 v95, 1.0, v95
	v_rcp_f32_e32 v91, v91
	v_add_f32_e32 v94, 1.0, v94
	v_rcp_f32_e32 v96, v95
	v_add_f32_e32 v95, 1.0, v97
	v_add_f32_e32 v97, 1.0, v98
	v_rcp_f32_e32 v94, v94
	v_rcp_f32_e32 v95, v95
	v_rcp_f32_e32 v97, v97
	v_pk_mul_f32 v[84:85], v[84:85], v[88:89]
	v_pk_mul_f32 v[88:89], v[80:81], v[90:91]
	v_cvt_pk_bf16_f32 v80, v84, v85
	v_lshl_add_u64 v[84:85], v[92:93], 0, v[112:113]
	v_pk_mul_f32 v[86:87], v[86:87], v[94:95]
	v_pk_mul_f32 v[90:91], v[82:83], v[96:97]
	v_lshl_add_u64 v[84:85], v[84:85], 0, s[20:21]
	v_cvt_pk_bf16_f32 v81, v86, v87
	v_cvt_pk_bf16_f32 v82, v88, v89
	v_cvt_pk_bf16_f32 v83, v90, v91
	v_lshl_add_u64 v[84:85], v[84:85], 0, v[136:137]
	global_store_dwordx4 v[84:85], v[80:83], off sc1
	v_mul_f32_e32 v84, 0x3d372713, v77
	v_mul_f32_e32 v84, v77, v84
	v_fma_f32 v84, v77, v84, v77
	v_mul_f32_e32 v84, 0x3fcc422a, v84
	v_mul_f32_e32 v83, 0x3d372713, v72
	v_mul_f32_e32 v84, 0xbfb8aa3b, v84
	v_mul_f32_e32 v83, v72, v83
	v_exp_f32_e32 v85, v84
	v_mul_f32_e32 v84, 0x3d372713, v73
	v_fma_f32 v83, v72, v83, v72
	v_mul_f32_e32 v84, v73, v84
	v_mul_f32_e32 v83, 0x3fcc422a, v83
	v_fma_f32 v84, v73, v84, v73
	v_mul_f32_e32 v83, 0xbfb8aa3b, v83
	v_mul_f32_e32 v84, 0x3fcc422a, v84
	v_exp_f32_e32 v83, v83
	v_mul_f32_e32 v84, 0xbfb8aa3b, v84
	v_exp_f32_e32 v86, v84
	v_mul_f32_e32 v88, 0x3d372713, v79
	v_mul_f32_e32 v88, v79, v88
	v_mul_f32_e32 v82, 0x3d372713, v76
	v_add_f32_e32 v83, 1.0, v83
	v_mul_f32_e32 v87, 0x3d372713, v74
	v_fma_f32 v88, v79, v88, v79
	v_mul_f32_e32 v82, v76, v82
	v_rcp_f32_e32 v84, v83
	v_add_f32_e32 v83, 1.0, v85
	v_add_f32_e32 v85, 1.0, v86
	v_mul_f32_e32 v86, 0x3d372713, v78
	v_mul_f32_e32 v87, v74, v87
	v_mul_f32_e32 v88, 0x3fcc422a, v88
	v_fma_f32 v82, v76, v82, v76
	v_mul_f32_e32 v86, v78, v86
	v_fma_f32 v87, v74, v87, v74
	v_mul_f32_e32 v88, 0xbfb8aa3b, v88
	v_mul_f32_e32 v82, 0x3fcc422a, v82
	v_fma_f32 v86, v78, v86, v78
	v_mul_f32_e32 v87, 0x3fcc422a, v87
	v_exp_f32_e32 v89, v88
	v_mul_f32_e32 v88, 0x3d372713, v75
	v_mul_f32_e32 v82, 0xbfb8aa3b, v82
	v_mul_f32_e32 v86, 0x3fcc422a, v86
	v_mul_f32_e32 v87, 0xbfb8aa3b, v87
	v_mul_f32_e32 v88, v75, v88
	v_exp_f32_e32 v82, v82
	v_mul_f32_e32 v86, 0xbfb8aa3b, v86
	v_exp_f32_e32 v87, v87
	v_fma_f32 v88, v75, v88, v75
	v_exp_f32_e32 v86, v86
	v_mul_f32_e32 v88, 0x3fcc422a, v88
	v_mul_f32_e32 v88, 0xbfb8aa3b, v88
	v_exp_f32_e32 v90, v88
	v_add_f32_e32 v82, 1.0, v82
	v_add_f32_e32 v87, 1.0, v87
	v_rcp_f32_e32 v82, v82
	v_rcp_f32_e32 v83, v83
	v_add_f32_e32 v86, 1.0, v86
	v_rcp_f32_e32 v88, v87
	v_add_f32_e32 v87, 1.0, v89
	v_rcp_f32_e32 v85, v85
	v_rcp_f32_e32 v86, v86
	v_rcp_f32_e32 v87, v87
	v_or_b32_e32 v80, 48, v142
	v_add_f32_e32 v89, 1.0, v90
	v_ashrrev_i32_e32 v81, 31, v80
	v_rcp_f32_e32 v89, v89
	v_lshlrev_b64 v[80:81], 15, v[80:81]
	v_pk_mul_f32 v[76:77], v[76:77], v[82:83]
	v_pk_mul_f32 v[82:83], v[72:73], v[84:85]
	v_pk_mul_f32 v[78:79], v[78:79], v[86:87]
	v_cvt_pk_bf16_f32 v72, v76, v77
	v_lshl_add_u64 v[76:77], s[84:85], 0, v[80:81]
	v_cvt_pk_bf16_f32 v73, v78, v79
	v_lshl_add_u64 v[78:79], v[76:77], 0, v[122:123]
	v_pk_mul_f32 v[84:85], v[74:75], v[88:89]
	v_lshl_add_u64 v[78:79], v[78:79], 0, s[20:21]
	v_cvt_pk_bf16_f32 v74, v82, v83
	v_cvt_pk_bf16_f32 v75, v84, v85
	v_lshl_add_u64 v[78:79], v[78:79], 0, v[136:137]
	v_mul_f32_e32 v80, 0x3d372713, v68
	global_store_dwordx4 v[78:79], v[72:75], off sc1
	v_mul_f32_e32 v80, v68, v80
	v_fma_f32 v80, v68, v80, v68
	v_mul_f32_e32 v74, 0x3d372713, v69
	v_mul_f32_e32 v74, v69, v74
	v_fma_f32 v74, v69, v74, v69
	v_mul_f32_e32 v80, 0x3fcc422a, v80
	v_mul_f32_e32 v74, 0x3fcc422a, v74
	v_mul_f32_e32 v80, 0xbfb8aa3b, v80
	v_mul_f32_e32 v81, 0x3d372713, v64
	v_mul_f32_e32 v74, 0xbfb8aa3b, v74
	v_exp_f32_e32 v80, v80
	v_mul_f32_e32 v81, v64, v81
	v_exp_f32_e32 v75, v74
	v_mul_f32_e32 v74, 0x3d372713, v65
	v_fma_f32 v81, v64, v81, v64
	v_mul_f32_e32 v74, v65, v74
	v_mul_f32_e32 v81, 0x3fcc422a, v81
	v_fma_f32 v74, v65, v74, v65
	v_mul_f32_e32 v81, 0xbfb8aa3b, v81
	v_mul_f32_e32 v74, 0x3fcc422a, v74
	v_exp_f32_e32 v81, v81
	v_add_f32_e32 v72, 1.0, v80
	v_mul_f32_e32 v74, 0xbfb8aa3b, v74
	v_mul_f32_e32 v80, 0x3d372713, v71
	v_exp_f32_e32 v78, v74
	v_mul_f32_e32 v80, v71, v80
	v_fma_f32 v80, v71, v80, v71
	v_mul_f32_e32 v80, 0x3fcc422a, v80
	v_add_f32_e32 v73, 1.0, v81
	v_mul_f32_e32 v79, 0x3d372713, v66
	v_mul_f32_e32 v80, 0xbfb8aa3b, v80
	v_rcp_f32_e32 v74, v73
	v_add_f32_e32 v73, 1.0, v75
	v_add_f32_e32 v75, 1.0, v78
	v_mul_f32_e32 v78, 0x3d372713, v70
	v_mul_f32_e32 v79, v66, v79
	v_exp_f32_e32 v81, v80
	v_mul_f32_e32 v80, 0x3d372713, v67
	v_mul_f32_e32 v78, v70, v78
	v_fma_f32 v79, v66, v79, v66
	v_mul_f32_e32 v80, v67, v80
	v_fma_f32 v78, v70, v78, v70
	v_mul_f32_e32 v79, 0x3fcc422a, v79
	v_fma_f32 v80, v67, v80, v67
	v_mul_f32_e32 v78, 0x3fcc422a, v78
	v_mul_f32_e32 v79, 0xbfb8aa3b, v79
	v_mul_f32_e32 v80, 0x3fcc422a, v80
	v_mul_f32_e32 v78, 0xbfb8aa3b, v78
	v_exp_f32_e32 v79, v79
	v_mul_f32_e32 v80, 0xbfb8aa3b, v80
	v_exp_f32_e32 v78, v78
	v_exp_f32_e32 v82, v80
	v_rcp_f32_e32 v72, v72
	v_rcp_f32_e32 v73, v73
	v_add_f32_e32 v79, 1.0, v79
	v_rcp_f32_e32 v75, v75
	v_add_f32_e32 v78, 1.0, v78
	v_rcp_f32_e32 v80, v79
	v_add_f32_e32 v79, 1.0, v81
	v_add_f32_e32 v81, 1.0, v82
	v_rcp_f32_e32 v78, v78
	v_rcp_f32_e32 v79, v79
	v_rcp_f32_e32 v81, v81
	v_pk_mul_f32 v[68:69], v[68:69], v[72:73]
	v_pk_mul_f32 v[72:73], v[64:65], v[74:75]
	v_cvt_pk_bf16_f32 v64, v68, v69
	v_lshl_add_u64 v[68:69], v[76:77], 0, v[112:113]
	v_pk_mul_f32 v[70:71], v[70:71], v[78:79]
	v_pk_mul_f32 v[74:75], v[66:67], v[80:81]
	v_lshl_add_u64 v[68:69], v[68:69], 0, s[20:21]
	v_cvt_pk_bf16_f32 v65, v70, v71
	v_cvt_pk_bf16_f32 v66, v72, v73
	v_cvt_pk_bf16_f32 v67, v74, v75
	v_lshl_add_u64 v[68:69], v[68:69], 0, v[136:137]
	global_store_dwordx4 v[68:69], v[64:67], off sc1
	v_mul_f32_e32 v70, 0x3d372713, v60
	v_mul_f32_e32 v70, v60, v70
	v_mul_f32_e32 v66, 0x3d372713, v61
	v_mul_f32_e32 v66, v61, v66
	v_fma_f32 v66, v61, v66, v61
	v_mul_f32_e32 v66, 0x3fcc422a, v66
	v_fma_f32 v70, v60, v70, v60
	v_mul_f32_e32 v71, 0x3d372713, v56
	v_mul_f32_e32 v66, 0xbfb8aa3b, v66
	v_mul_f32_e32 v70, 0x3fcc422a, v70
	v_mul_f32_e32 v71, v56, v71
	v_exp_f32_e32 v67, v66
	v_mul_f32_e32 v66, 0x3d372713, v57
	v_mul_f32_e32 v70, 0xbfb8aa3b, v70
	v_fma_f32 v71, v56, v71, v56
	v_mul_f32_e32 v66, v57, v66
	v_exp_f32_e32 v70, v70
	v_mul_f32_e32 v71, 0x3fcc422a, v71
	v_fma_f32 v66, v57, v66, v57
	v_mul_f32_e32 v71, 0xbfb8aa3b, v71
	v_mul_f32_e32 v66, 0x3fcc422a, v66
	v_exp_f32_e32 v71, v71
	v_mul_f32_e32 v66, 0xbfb8aa3b, v66
	v_exp_f32_e32 v68, v66
	v_add_f32_e32 v64, 1.0, v70
	v_mul_f32_e32 v70, 0x3d372713, v63
	v_mul_f32_e32 v70, v63, v70
	v_add_f32_e32 v65, 1.0, v71
	v_mul_f32_e32 v69, 0x3d372713, v58
	v_fma_f32 v70, v63, v70, v63
	v_rcp_f32_e32 v66, v65
	v_add_f32_e32 v65, 1.0, v67
	v_add_f32_e32 v67, 1.0, v68
	v_mul_f32_e32 v68, 0x3d372713, v62
	v_mul_f32_e32 v69, v58, v69
	v_mul_f32_e32 v70, 0x3fcc422a, v70
	v_mul_f32_e32 v68, v62, v68
	v_fma_f32 v69, v58, v69, v58
	v_mul_f32_e32 v70, 0xbfb8aa3b, v70
	v_fma_f32 v68, v62, v68, v62
	v_mul_f32_e32 v69, 0x3fcc422a, v69
	v_exp_f32_e32 v71, v70
	v_mul_f32_e32 v70, 0x3d372713, v59
	v_mul_f32_e32 v68, 0x3fcc422a, v68
	v_mul_f32_e32 v69, 0xbfb8aa3b, v69
	v_mul_f32_e32 v70, v59, v70
	v_mul_f32_e32 v68, 0xbfb8aa3b, v68
	v_exp_f32_e32 v69, v69
	v_fma_f32 v70, v59, v70, v59
	v_exp_f32_e32 v68, v68
	v_mul_f32_e32 v70, 0x3fcc422a, v70
	v_mul_f32_e32 v70, 0xbfb8aa3b, v70
	v_exp_f32_e32 v72, v70
	v_add_f32_e32 v69, 1.0, v69
	v_rcp_f32_e32 v64, v64
	v_rcp_f32_e32 v65, v65
	v_add_f32_e32 v68, 1.0, v68
	v_rcp_f32_e32 v70, v69
	v_add_f32_e32 v69, 1.0, v71
	v_rcp_f32_e32 v67, v67
	v_rcp_f32_e32 v68, v68
	v_rcp_f32_e32 v69, v69
	v_add_f32_e32 v71, 1.0, v72
	v_rcp_f32_e32 v71, v71
	v_pk_mul_f32 v[60:61], v[60:61], v[64:65]
	s_mov_b64 s[22:23], 0x400000
	v_pk_mul_f32 v[64:65], v[56:57], v[66:67]
	v_pk_mul_f32 v[62:63], v[62:63], v[68:69]
	v_cvt_pk_bf16_f32 v56, v60, v61
	v_lshl_add_u64 v[60:61], v[120:121], 0, s[22:23]
	v_cvt_pk_bf16_f32 v57, v62, v63
	v_lshl_add_u64 v[62:63], v[60:61], 0, v[122:123]
	v_pk_mul_f32 v[66:67], v[58:59], v[70:71]
	v_lshl_add_u64 v[62:63], v[62:63], 0, s[20:21]
	v_cvt_pk_bf16_f32 v58, v64, v65
	v_cvt_pk_bf16_f32 v59, v66, v67
	v_lshl_add_u64 v[62:63], v[62:63], 0, v[136:137]
	v_mul_f32_e32 v64, 0x3d372713, v52
	global_store_dwordx4 v[62:63], v[56:59], off sc1
	v_mul_f32_e32 v64, v52, v64
	v_fma_f32 v64, v52, v64, v52
	v_mul_f32_e32 v58, 0x3d372713, v53
	v_mul_f32_e32 v58, v53, v58
	v_fma_f32 v58, v53, v58, v53
	v_mul_f32_e32 v64, 0x3fcc422a, v64
	v_mul_f32_e32 v58, 0x3fcc422a, v58
	v_mul_f32_e32 v64, 0xbfb8aa3b, v64
	v_mul_f32_e32 v65, 0x3d372713, v48
	v_mul_f32_e32 v58, 0xbfb8aa3b, v58
	v_exp_f32_e32 v64, v64
	v_mul_f32_e32 v65, v48, v65
	v_exp_f32_e32 v59, v58
	v_mul_f32_e32 v58, 0x3d372713, v49
	v_fma_f32 v65, v48, v65, v48
	v_mul_f32_e32 v58, v49, v58
	v_mul_f32_e32 v65, 0x3fcc422a, v65
	v_fma_f32 v58, v49, v58, v49
	v_mul_f32_e32 v65, 0xbfb8aa3b, v65
	v_mul_f32_e32 v58, 0x3fcc422a, v58
	v_exp_f32_e32 v65, v65
	v_add_f32_e32 v56, 1.0, v64
	v_mul_f32_e32 v58, 0xbfb8aa3b, v58
	v_mul_f32_e32 v64, 0x3d372713, v55
	v_exp_f32_e32 v62, v58
	v_mul_f32_e32 v64, v55, v64
	v_fma_f32 v64, v55, v64, v55
	v_mul_f32_e32 v64, 0x3fcc422a, v64
	v_add_f32_e32 v57, 1.0, v65
	v_mul_f32_e32 v63, 0x3d372713, v50
	v_mul_f32_e32 v64, 0xbfb8aa3b, v64
	v_rcp_f32_e32 v58, v57
	v_add_f32_e32 v57, 1.0, v59
	v_add_f32_e32 v59, 1.0, v62
	v_mul_f32_e32 v62, 0x3d372713, v54
	v_mul_f32_e32 v63, v50, v63
	v_exp_f32_e32 v65, v64
	v_mul_f32_e32 v64, 0x3d372713, v51
	v_mul_f32_e32 v62, v54, v62
	v_fma_f32 v63, v50, v63, v50
	v_mul_f32_e32 v64, v51, v64
	v_fma_f32 v62, v54, v62, v54
	v_mul_f32_e32 v63, 0x3fcc422a, v63
	v_fma_f32 v64, v51, v64, v51
	v_mul_f32_e32 v62, 0x3fcc422a, v62
	v_mul_f32_e32 v63, 0xbfb8aa3b, v63
	v_mul_f32_e32 v64, 0x3fcc422a, v64
	v_mul_f32_e32 v62, 0xbfb8aa3b, v62
	v_exp_f32_e32 v63, v63
	v_mul_f32_e32 v64, 0xbfb8aa3b, v64
	v_exp_f32_e32 v62, v62
	v_exp_f32_e32 v66, v64
	v_rcp_f32_e32 v56, v56
	v_rcp_f32_e32 v57, v57
	v_add_f32_e32 v63, 1.0, v63
	v_rcp_f32_e32 v59, v59
	v_add_f32_e32 v62, 1.0, v62
	v_rcp_f32_e32 v64, v63
	v_add_f32_e32 v63, 1.0, v65
	v_add_f32_e32 v65, 1.0, v66
	v_rcp_f32_e32 v62, v62
	v_rcp_f32_e32 v63, v63
	v_rcp_f32_e32 v65, v65
	v_pk_mul_f32 v[52:53], v[52:53], v[56:57]
	v_pk_mul_f32 v[56:57], v[48:49], v[58:59]
	v_cvt_pk_bf16_f32 v48, v52, v53
	v_lshl_add_u64 v[52:53], v[60:61], 0, v[112:113]
	v_pk_mul_f32 v[54:55], v[54:55], v[62:63]
	v_pk_mul_f32 v[58:59], v[50:51], v[64:65]
	v_lshl_add_u64 v[52:53], v[52:53], 0, s[20:21]
	v_cvt_pk_bf16_f32 v49, v54, v55
	v_cvt_pk_bf16_f32 v50, v56, v57
	v_cvt_pk_bf16_f32 v51, v58, v59
	v_lshl_add_u64 v[52:53], v[52:53], 0, v[136:137]
	global_store_dwordx4 v[52:53], v[48:51], off sc1
	v_mul_f32_e32 v54, 0x3d372713, v44
	v_mul_f32_e32 v54, v44, v54
	v_mul_f32_e32 v50, 0x3d372713, v45
	v_mul_f32_e32 v50, v45, v50
	v_fma_f32 v50, v45, v50, v45
	v_mul_f32_e32 v50, 0x3fcc422a, v50
	v_fma_f32 v54, v44, v54, v44
	v_mul_f32_e32 v55, 0x3d372713, v40
	v_mul_f32_e32 v50, 0xbfb8aa3b, v50
	v_mul_f32_e32 v54, 0x3fcc422a, v54
	v_mul_f32_e32 v55, v40, v55
	v_exp_f32_e32 v51, v50
	v_mul_f32_e32 v50, 0x3d372713, v41
	v_mul_f32_e32 v54, 0xbfb8aa3b, v54
	v_fma_f32 v55, v40, v55, v40
	v_mul_f32_e32 v50, v41, v50
	v_exp_f32_e32 v54, v54
	v_mul_f32_e32 v55, 0x3fcc422a, v55
	v_fma_f32 v50, v41, v50, v41
	v_mul_f32_e32 v55, 0xbfb8aa3b, v55
	v_mul_f32_e32 v50, 0x3fcc422a, v50
	v_exp_f32_e32 v55, v55
	v_mul_f32_e32 v50, 0xbfb8aa3b, v50
	v_exp_f32_e32 v52, v50
	v_add_f32_e32 v48, 1.0, v54
	v_mul_f32_e32 v54, 0x3d372713, v47
	v_mul_f32_e32 v54, v47, v54
	v_add_f32_e32 v49, 1.0, v55
	v_mul_f32_e32 v53, 0x3d372713, v42
	v_fma_f32 v54, v47, v54, v47
	v_rcp_f32_e32 v50, v49
	v_add_f32_e32 v49, 1.0, v51
	v_add_f32_e32 v51, 1.0, v52
	v_mul_f32_e32 v52, 0x3d372713, v46
	v_mul_f32_e32 v53, v42, v53
	v_mul_f32_e32 v54, 0x3fcc422a, v54
	v_mul_f32_e32 v52, v46, v52
	v_fma_f32 v53, v42, v53, v42
	v_mul_f32_e32 v54, 0xbfb8aa3b, v54
	v_fma_f32 v52, v46, v52, v46
	v_mul_f32_e32 v53, 0x3fcc422a, v53
	v_exp_f32_e32 v55, v54
	v_mul_f32_e32 v54, 0x3d372713, v43
	v_mul_f32_e32 v52, 0x3fcc422a, v52
	v_mul_f32_e32 v53, 0xbfb8aa3b, v53
	v_mul_f32_e32 v54, v43, v54
	v_mul_f32_e32 v52, 0xbfb8aa3b, v52
	v_exp_f32_e32 v53, v53
	v_fma_f32 v54, v43, v54, v43
	v_exp_f32_e32 v52, v52
	v_mul_f32_e32 v54, 0x3fcc422a, v54
	v_mul_f32_e32 v54, 0xbfb8aa3b, v54
	v_exp_f32_e32 v56, v54
	v_add_f32_e32 v53, 1.0, v53
	v_rcp_f32_e32 v48, v48
	v_rcp_f32_e32 v49, v49
	v_add_f32_e32 v52, 1.0, v52
	v_rcp_f32_e32 v54, v53
	v_add_f32_e32 v53, 1.0, v55
	v_rcp_f32_e32 v51, v51
	v_rcp_f32_e32 v52, v52
	v_rcp_f32_e32 v53, v53
	v_add_f32_e32 v55, 1.0, v56
	v_rcp_f32_e32 v55, v55
	v_pk_mul_f32 v[44:45], v[44:45], v[48:49]
	s_mov_b64 s[22:23], 0x480000
	v_pk_mul_f32 v[48:49], v[40:41], v[50:51]
	v_pk_mul_f32 v[46:47], v[46:47], v[52:53]
	v_cvt_pk_bf16_f32 v40, v44, v45
	v_lshl_add_u64 v[44:45], v[120:121], 0, s[22:23]
	v_cvt_pk_bf16_f32 v41, v46, v47
	v_lshl_add_u64 v[46:47], v[44:45], 0, v[122:123]
	v_pk_mul_f32 v[50:51], v[42:43], v[54:55]
	v_lshl_add_u64 v[46:47], v[46:47], 0, s[20:21]
	v_cvt_pk_bf16_f32 v42, v48, v49
	v_cvt_pk_bf16_f32 v43, v50, v51
	v_lshl_add_u64 v[46:47], v[46:47], 0, v[136:137]
	v_mul_f32_e32 v48, 0x3d372713, v36
	global_store_dwordx4 v[46:47], v[40:43], off sc1
	v_mul_f32_e32 v48, v36, v48
	v_fma_f32 v48, v36, v48, v36
	v_mul_f32_e32 v42, 0x3d372713, v37
	v_mul_f32_e32 v42, v37, v42
	v_fma_f32 v42, v37, v42, v37
	v_mul_f32_e32 v48, 0x3fcc422a, v48
	v_mul_f32_e32 v42, 0x3fcc422a, v42
	v_mul_f32_e32 v48, 0xbfb8aa3b, v48
	v_mul_f32_e32 v49, 0x3d372713, v32
	v_mul_f32_e32 v42, 0xbfb8aa3b, v42
	v_exp_f32_e32 v48, v48
	v_mul_f32_e32 v49, v32, v49
	v_exp_f32_e32 v43, v42
	v_mul_f32_e32 v42, 0x3d372713, v33
	v_fma_f32 v49, v32, v49, v32
	v_mul_f32_e32 v42, v33, v42
	v_mul_f32_e32 v49, 0x3fcc422a, v49
	v_fma_f32 v42, v33, v42, v33
	v_mul_f32_e32 v49, 0xbfb8aa3b, v49
	v_mul_f32_e32 v42, 0x3fcc422a, v42
	v_exp_f32_e32 v49, v49
	v_add_f32_e32 v40, 1.0, v48
	v_mul_f32_e32 v42, 0xbfb8aa3b, v42
	v_mul_f32_e32 v48, 0x3d372713, v39
	v_exp_f32_e32 v46, v42
	v_mul_f32_e32 v48, v39, v48
	v_fma_f32 v48, v39, v48, v39
	v_mul_f32_e32 v48, 0x3fcc422a, v48
	v_add_f32_e32 v41, 1.0, v49
	v_mul_f32_e32 v47, 0x3d372713, v34
	v_mul_f32_e32 v48, 0xbfb8aa3b, v48
	v_rcp_f32_e32 v42, v41
	v_add_f32_e32 v41, 1.0, v43
	v_add_f32_e32 v43, 1.0, v46
	v_mul_f32_e32 v46, 0x3d372713, v38
	v_mul_f32_e32 v47, v34, v47
	v_exp_f32_e32 v49, v48
	v_mul_f32_e32 v48, 0x3d372713, v35
	v_mul_f32_e32 v46, v38, v46
	v_fma_f32 v47, v34, v47, v34
	v_mul_f32_e32 v48, v35, v48
	v_fma_f32 v46, v38, v46, v38
	v_mul_f32_e32 v47, 0x3fcc422a, v47
	v_fma_f32 v48, v35, v48, v35
	v_mul_f32_e32 v46, 0x3fcc422a, v46
	v_mul_f32_e32 v47, 0xbfb8aa3b, v47
	v_mul_f32_e32 v48, 0x3fcc422a, v48
	v_mul_f32_e32 v46, 0xbfb8aa3b, v46
	v_exp_f32_e32 v47, v47
	v_mul_f32_e32 v48, 0xbfb8aa3b, v48
	v_exp_f32_e32 v46, v46
	v_exp_f32_e32 v50, v48
	v_rcp_f32_e32 v40, v40
	v_rcp_f32_e32 v41, v41
	v_add_f32_e32 v47, 1.0, v47
	v_rcp_f32_e32 v43, v43
	v_add_f32_e32 v46, 1.0, v46
	v_rcp_f32_e32 v48, v47
	v_add_f32_e32 v47, 1.0, v49
	v_add_f32_e32 v49, 1.0, v50
	v_rcp_f32_e32 v46, v46
	v_rcp_f32_e32 v47, v47
	v_rcp_f32_e32 v49, v49
	v_pk_mul_f32 v[36:37], v[36:37], v[40:41]
	v_pk_mul_f32 v[40:41], v[32:33], v[42:43]
	v_cvt_pk_bf16_f32 v32, v36, v37
	v_lshl_add_u64 v[36:37], v[44:45], 0, v[112:113]
	v_pk_mul_f32 v[38:39], v[38:39], v[46:47]
	v_pk_mul_f32 v[42:43], v[34:35], v[48:49]
	v_lshl_add_u64 v[36:37], v[36:37], 0, s[20:21]
	v_cvt_pk_bf16_f32 v33, v38, v39
	v_cvt_pk_bf16_f32 v34, v40, v41
	v_cvt_pk_bf16_f32 v35, v42, v43
	v_lshl_add_u64 v[36:37], v[36:37], 0, v[136:137]
	global_store_dwordx4 v[36:37], v[32:35], off sc1
	v_mul_f32_e32 v38, 0x3d372713, v28
	v_mul_f32_e32 v38, v28, v38
	v_mul_f32_e32 v34, 0x3d372713, v29
	v_mul_f32_e32 v34, v29, v34
	v_fma_f32 v34, v29, v34, v29
	v_mul_f32_e32 v34, 0x3fcc422a, v34
	v_fma_f32 v38, v28, v38, v28
	v_mul_f32_e32 v39, 0x3d372713, v24
	v_mul_f32_e32 v34, 0xbfb8aa3b, v34
	v_mul_f32_e32 v38, 0x3fcc422a, v38
	v_mul_f32_e32 v39, v24, v39
	v_exp_f32_e32 v35, v34
	v_mul_f32_e32 v34, 0x3d372713, v25
	v_mul_f32_e32 v38, 0xbfb8aa3b, v38
	v_fma_f32 v39, v24, v39, v24
	v_mul_f32_e32 v34, v25, v34
	v_exp_f32_e32 v38, v38
	v_mul_f32_e32 v39, 0x3fcc422a, v39
	v_fma_f32 v34, v25, v34, v25
	v_mul_f32_e32 v39, 0xbfb8aa3b, v39
	v_mul_f32_e32 v34, 0x3fcc422a, v34
	v_exp_f32_e32 v39, v39
	v_mul_f32_e32 v34, 0xbfb8aa3b, v34
	v_exp_f32_e32 v36, v34
	v_add_f32_e32 v32, 1.0, v38
	v_mul_f32_e32 v38, 0x3d372713, v31
	v_mul_f32_e32 v38, v31, v38
	v_add_f32_e32 v33, 1.0, v39
	v_mul_f32_e32 v37, 0x3d372713, v26
	v_fma_f32 v38, v31, v38, v31
	v_rcp_f32_e32 v34, v33
	v_add_f32_e32 v33, 1.0, v35
	v_add_f32_e32 v35, 1.0, v36
	v_mul_f32_e32 v36, 0x3d372713, v30
	v_mul_f32_e32 v37, v26, v37
	v_mul_f32_e32 v38, 0x3fcc422a, v38
	v_mul_f32_e32 v36, v30, v36
	v_fma_f32 v37, v26, v37, v26
	v_mul_f32_e32 v38, 0xbfb8aa3b, v38
	v_fma_f32 v36, v30, v36, v30
	v_mul_f32_e32 v37, 0x3fcc422a, v37
	v_exp_f32_e32 v39, v38
	v_mul_f32_e32 v38, 0x3d372713, v27
	v_mul_f32_e32 v36, 0x3fcc422a, v36
	v_mul_f32_e32 v37, 0xbfb8aa3b, v37
	v_mul_f32_e32 v38, v27, v38
	v_mul_f32_e32 v36, 0xbfb8aa3b, v36
	v_exp_f32_e32 v37, v37
	v_fma_f32 v38, v27, v38, v27
	v_exp_f32_e32 v36, v36
	v_mul_f32_e32 v38, 0x3fcc422a, v38
	v_mul_f32_e32 v38, 0xbfb8aa3b, v38
	v_exp_f32_e32 v40, v38
	v_add_f32_e32 v37, 1.0, v37
	v_rcp_f32_e32 v32, v32
	v_rcp_f32_e32 v33, v33
	v_add_f32_e32 v36, 1.0, v36
	v_rcp_f32_e32 v38, v37
	v_add_f32_e32 v37, 1.0, v39
	v_rcp_f32_e32 v35, v35
	v_rcp_f32_e32 v36, v36
	v_rcp_f32_e32 v37, v37
	v_add_f32_e32 v39, 1.0, v40
	v_rcp_f32_e32 v39, v39
	v_pk_mul_f32 v[28:29], v[28:29], v[32:33]
	v_pk_mul_f32 v[32:33], v[24:25], v[34:35]
	v_pk_mul_f32 v[30:31], v[30:31], v[36:37]
	v_cvt_pk_bf16_f32 v24, v28, v29
	v_lshl_add_u64 v[28:29], v[120:121], 0, s[10:11]
	v_cvt_pk_bf16_f32 v25, v30, v31
	v_lshl_add_u64 v[30:31], v[28:29], 0, v[122:123]
	v_pk_mul_f32 v[34:35], v[26:27], v[38:39]
	v_lshl_add_u64 v[30:31], v[30:31], 0, s[20:21]
	v_cvt_pk_bf16_f32 v26, v32, v33
	v_cvt_pk_bf16_f32 v27, v34, v35
	v_lshl_add_u64 v[30:31], v[30:31], 0, v[136:137]
	v_mul_f32_e32 v32, 0x3d372713, v20
	global_store_dwordx4 v[30:31], v[24:27], off sc1
	v_mul_f32_e32 v32, v20, v32
	v_fma_f32 v32, v20, v32, v20
	v_mul_f32_e32 v26, 0x3d372713, v21
	v_mul_f32_e32 v26, v21, v26
	v_fma_f32 v26, v21, v26, v21
	v_mul_f32_e32 v32, 0x3fcc422a, v32
	v_mul_f32_e32 v26, 0x3fcc422a, v26
	v_mul_f32_e32 v32, 0xbfb8aa3b, v32
	v_mul_f32_e32 v33, 0x3d372713, v16
	v_mul_f32_e32 v26, 0xbfb8aa3b, v26
	v_exp_f32_e32 v32, v32
	v_mul_f32_e32 v33, v16, v33
	v_exp_f32_e32 v27, v26
	v_mul_f32_e32 v26, 0x3d372713, v17
	v_fma_f32 v33, v16, v33, v16
	v_mul_f32_e32 v26, v17, v26
	v_mul_f32_e32 v33, 0x3fcc422a, v33
	v_fma_f32 v26, v17, v26, v17
	v_mul_f32_e32 v33, 0xbfb8aa3b, v33
	v_mul_f32_e32 v26, 0x3fcc422a, v26
	v_exp_f32_e32 v33, v33
	v_add_f32_e32 v24, 1.0, v32
	v_mul_f32_e32 v26, 0xbfb8aa3b, v26
	v_mul_f32_e32 v32, 0x3d372713, v23
	v_exp_f32_e32 v30, v26
	v_mul_f32_e32 v32, v23, v32
	v_fma_f32 v32, v23, v32, v23
	v_mul_f32_e32 v32, 0x3fcc422a, v32
	v_add_f32_e32 v25, 1.0, v33
	v_mul_f32_e32 v31, 0x3d372713, v18
	v_mul_f32_e32 v32, 0xbfb8aa3b, v32
	v_rcp_f32_e32 v26, v25
	v_add_f32_e32 v25, 1.0, v27
	v_add_f32_e32 v27, 1.0, v30
	v_mul_f32_e32 v30, 0x3d372713, v22
	v_mul_f32_e32 v31, v18, v31
	v_exp_f32_e32 v33, v32
	v_mul_f32_e32 v32, 0x3d372713, v19
	v_mul_f32_e32 v30, v22, v30
	v_fma_f32 v31, v18, v31, v18
	v_mul_f32_e32 v32, v19, v32
	v_fma_f32 v30, v22, v30, v22
	v_mul_f32_e32 v31, 0x3fcc422a, v31
	v_fma_f32 v32, v19, v32, v19
	v_mul_f32_e32 v30, 0x3fcc422a, v30
	v_mul_f32_e32 v31, 0xbfb8aa3b, v31
	v_mul_f32_e32 v32, 0x3fcc422a, v32
	v_mul_f32_e32 v30, 0xbfb8aa3b, v30
	v_exp_f32_e32 v31, v31
	v_mul_f32_e32 v32, 0xbfb8aa3b, v32
	v_exp_f32_e32 v30, v30
	v_exp_f32_e32 v34, v32
	v_rcp_f32_e32 v24, v24
	v_rcp_f32_e32 v25, v25
	v_add_f32_e32 v31, 1.0, v31
	v_rcp_f32_e32 v27, v27
	v_add_f32_e32 v30, 1.0, v30
	v_rcp_f32_e32 v32, v31
	v_add_f32_e32 v31, 1.0, v33
	v_add_f32_e32 v33, 1.0, v34
	v_rcp_f32_e32 v30, v30
	v_rcp_f32_e32 v31, v31
	v_rcp_f32_e32 v33, v33
	v_pk_mul_f32 v[20:21], v[20:21], v[24:25]
	v_pk_mul_f32 v[24:25], v[16:17], v[26:27]
	v_cvt_pk_bf16_f32 v16, v20, v21
	v_lshl_add_u64 v[20:21], v[28:29], 0, v[112:113]
	v_pk_mul_f32 v[22:23], v[22:23], v[30:31]
	v_pk_mul_f32 v[26:27], v[18:19], v[32:33]
	v_lshl_add_u64 v[20:21], v[20:21], 0, s[20:21]
	v_cvt_pk_bf16_f32 v17, v22, v23
	v_cvt_pk_bf16_f32 v18, v24, v25
	v_cvt_pk_bf16_f32 v19, v26, v27
	v_lshl_add_u64 v[20:21], v[20:21], 0, v[136:137]
	global_store_dwordx4 v[20:21], v[16:19], off sc1
	v_mul_f32_e32 v22, 0x3d372713, v12
	v_mul_f32_e32 v22, v12, v22
	v_mul_f32_e32 v18, 0x3d372713, v13
	v_mul_f32_e32 v18, v13, v18
	v_fma_f32 v18, v13, v18, v13
	v_mul_f32_e32 v18, 0x3fcc422a, v18
	v_fma_f32 v22, v12, v22, v12
	v_mul_f32_e32 v23, 0x3d372713, v8
	v_mul_f32_e32 v18, 0xbfb8aa3b, v18
	v_mul_f32_e32 v22, 0x3fcc422a, v22
	v_mul_f32_e32 v23, v8, v23
	v_exp_f32_e32 v19, v18
	v_mul_f32_e32 v18, 0x3d372713, v9
	v_mul_f32_e32 v22, 0xbfb8aa3b, v22
	v_fma_f32 v23, v8, v23, v8
	v_mul_f32_e32 v18, v9, v18
	v_exp_f32_e32 v22, v22
	v_mul_f32_e32 v23, 0x3fcc422a, v23
	v_fma_f32 v18, v9, v18, v9
	v_mul_f32_e32 v23, 0xbfb8aa3b, v23
	v_mul_f32_e32 v18, 0x3fcc422a, v18
	v_exp_f32_e32 v23, v23
	v_mul_f32_e32 v18, 0xbfb8aa3b, v18
	v_exp_f32_e32 v20, v18
	v_add_f32_e32 v16, 1.0, v22
	v_mul_f32_e32 v22, 0x3d372713, v15
	v_mul_f32_e32 v22, v15, v22
	v_add_f32_e32 v17, 1.0, v23
	v_mul_f32_e32 v21, 0x3d372713, v10
	v_fma_f32 v22, v15, v22, v15
	v_rcp_f32_e32 v18, v17
	v_add_f32_e32 v17, 1.0, v19
	v_add_f32_e32 v19, 1.0, v20
	v_mul_f32_e32 v20, 0x3d372713, v14
	v_mul_f32_e32 v21, v10, v21
	v_mul_f32_e32 v22, 0x3fcc422a, v22
	v_mul_f32_e32 v20, v14, v20
	v_fma_f32 v21, v10, v21, v10
	v_mul_f32_e32 v22, 0xbfb8aa3b, v22
	v_fma_f32 v20, v14, v20, v14
	v_mul_f32_e32 v21, 0x3fcc422a, v21
	v_exp_f32_e32 v23, v22
	v_mul_f32_e32 v22, 0x3d372713, v11
	v_mul_f32_e32 v20, 0x3fcc422a, v20
	v_mul_f32_e32 v21, 0xbfb8aa3b, v21
	v_mul_f32_e32 v22, v11, v22
	v_mul_f32_e32 v20, 0xbfb8aa3b, v20
	v_exp_f32_e32 v21, v21
	v_fma_f32 v22, v11, v22, v11
	v_exp_f32_e32 v20, v20
	v_mul_f32_e32 v22, 0x3fcc422a, v22
	v_mul_f32_e32 v22, 0xbfb8aa3b, v22
	v_exp_f32_e32 v24, v22
	v_add_f32_e32 v21, 1.0, v21
	v_rcp_f32_e32 v16, v16
	v_rcp_f32_e32 v17, v17
	v_add_f32_e32 v20, 1.0, v20
	v_rcp_f32_e32 v22, v21
	v_add_f32_e32 v21, 1.0, v23
	v_rcp_f32_e32 v19, v19
	v_rcp_f32_e32 v20, v20
	v_rcp_f32_e32 v21, v21
	v_add_f32_e32 v23, 1.0, v24
	v_rcp_f32_e32 v23, v23
	v_pk_mul_f32 v[12:13], v[12:13], v[16:17]
	v_pk_mul_f32 v[16:17], v[8:9], v[18:19]
	v_pk_mul_f32 v[14:15], v[14:15], v[20:21]
	v_cvt_pk_bf16_f32 v8, v12, v13
	v_lshl_add_u64 v[12:13], v[120:121], 0, s[12:13]
	v_cvt_pk_bf16_f32 v9, v14, v15
	v_lshl_add_u64 v[14:15], v[12:13], 0, v[122:123]
	v_pk_mul_f32 v[18:19], v[10:11], v[22:23]
	v_lshl_add_u64 v[14:15], v[14:15], 0, s[20:21]
	v_cvt_pk_bf16_f32 v10, v16, v17
	v_cvt_pk_bf16_f32 v11, v18, v19
	v_lshl_add_u64 v[14:15], v[14:15], 0, v[136:137]
	v_mul_f32_e32 v16, 0x3d372713, v4
	global_store_dwordx4 v[14:15], v[8:11], off sc1
	v_mul_f32_e32 v16, v4, v16
	v_fma_f32 v16, v4, v16, v4
	v_mul_f32_e32 v10, 0x3d372713, v5
	v_mul_f32_e32 v10, v5, v10
	v_fma_f32 v10, v5, v10, v5
	v_mul_f32_e32 v16, 0x3fcc422a, v16
	v_mul_f32_e32 v10, 0x3fcc422a, v10
	v_mul_f32_e32 v16, 0xbfb8aa3b, v16
	v_mul_f32_e32 v17, 0x3d372713, v0
	v_mul_f32_e32 v10, 0xbfb8aa3b, v10
	v_exp_f32_e32 v16, v16
	v_mul_f32_e32 v17, v0, v17
	v_exp_f32_e32 v11, v10
	v_mul_f32_e32 v10, 0x3d372713, v1
	v_fma_f32 v17, v0, v17, v0
	v_mul_f32_e32 v10, v1, v10
	v_mul_f32_e32 v17, 0x3fcc422a, v17
	v_fma_f32 v10, v1, v10, v1
	v_mul_f32_e32 v17, 0xbfb8aa3b, v17
	v_mul_f32_e32 v10, 0x3fcc422a, v10
	v_exp_f32_e32 v17, v17
	v_add_f32_e32 v8, 1.0, v16
	v_mul_f32_e32 v10, 0xbfb8aa3b, v10
	v_mul_f32_e32 v16, 0x3d372713, v7
	v_exp_f32_e32 v14, v10
	v_mul_f32_e32 v16, v7, v16
	v_fma_f32 v16, v7, v16, v7
	v_mul_f32_e32 v16, 0x3fcc422a, v16
	v_add_f32_e32 v9, 1.0, v17
	v_mul_f32_e32 v15, 0x3d372713, v2
	v_mul_f32_e32 v16, 0xbfb8aa3b, v16
	v_rcp_f32_e32 v10, v9
	v_add_f32_e32 v9, 1.0, v11
	v_add_f32_e32 v11, 1.0, v14
	v_mul_f32_e32 v14, 0x3d372713, v6
	v_mul_f32_e32 v15, v2, v15
	v_exp_f32_e32 v17, v16
	v_mul_f32_e32 v16, 0x3d372713, v3
	v_mul_f32_e32 v14, v6, v14
	v_fma_f32 v15, v2, v15, v2
	v_mul_f32_e32 v16, v3, v16
	v_fma_f32 v14, v6, v14, v6
	v_mul_f32_e32 v15, 0x3fcc422a, v15
	v_fma_f32 v16, v3, v16, v3
	v_mul_f32_e32 v14, 0x3fcc422a, v14
	v_mul_f32_e32 v15, 0xbfb8aa3b, v15
	v_mul_f32_e32 v16, 0x3fcc422a, v16
	v_mul_f32_e32 v14, 0xbfb8aa3b, v14
	v_exp_f32_e32 v15, v15
	v_mul_f32_e32 v16, 0xbfb8aa3b, v16
	v_exp_f32_e32 v14, v14
	v_exp_f32_e32 v18, v16
	v_rcp_f32_e32 v8, v8
	v_rcp_f32_e32 v9, v9
	v_add_f32_e32 v15, 1.0, v15
	v_rcp_f32_e32 v11, v11
	v_add_f32_e32 v14, 1.0, v14
	v_rcp_f32_e32 v16, v15
	v_add_f32_e32 v15, 1.0, v17
	v_add_f32_e32 v17, 1.0, v18
	v_rcp_f32_e32 v14, v14
	v_rcp_f32_e32 v15, v15
	v_rcp_f32_e32 v17, v17
	v_pk_mul_f32 v[4:5], v[4:5], v[8:9]
	v_pk_mul_f32 v[8:9], v[0:1], v[10:11]
	v_cvt_pk_bf16_f32 v0, v4, v5
	v_lshl_add_u64 v[4:5], v[12:13], 0, v[112:113]
	v_pk_mul_f32 v[6:7], v[6:7], v[14:15]
	v_pk_mul_f32 v[10:11], v[2:3], v[16:17]
	v_lshl_add_u64 v[4:5], v[4:5], 0, s[20:21]
	v_cvt_pk_bf16_f32 v1, v6, v7
	v_cvt_pk_bf16_f32 v2, v8, v9
	v_cvt_pk_bf16_f32 v3, v10, v11
	v_lshl_add_u64 v[4:5], v[4:5], 0, v[136:137]
	s_and_b64 vcc, exec, s[4:5]
	s_mov_b64 s[4:5], -1
	global_store_dwordx4 v[4:5], v[0:3], off sc1
	s_cbranch_vccnz .LBB0_560
	s_andn2_b64 vcc, exec, s[0:1]
	s_cbranch_vccnz .LBB0_559
	s_barrier
	s_branch .LBB0_559

.LBB0_577:
	v_log_f32_e32 v32, v96
	v_lshl_add_u64 v[252:253], s[0:1], 0, v[132:133]
	v_readlane_b32 s0, v254, 43
	v_readlane_b32 s1, v254, 44
	v_sub_f32_e32 v32, v32, v97
	v_mul_f32_e32 v33, v32, v203
	v_mul_f32_e32 v34, v32, v204
	v_mul_f32_e32 v35, v32, v205
	v_mul_f32_e32 v36, v32, v206
	v_exp_f32_e32 v33, v33
	v_exp_f32_e32 v37, v34
	v_exp_f32_e32 v34, v35
	v_exp_f32_e32 v35, v36
	v_mul_f32_e32 v33, v92, v33
	v_mul_f32_e32 v36, v93, v37
	v_cndmask_b32_e64 v33, v33, 0, s[4:5]
	v_cndmask_b32_e64 v36, 0, v36, s[6:7]
	v_pk_mul_f32 v[34:35], v[94:95], v[34:35]
	v_cvt_pk_bf16_f32 v36, v33, v36
	v_cvt_pk_bf16_f32 v33, v34, v35
	v_mul_f32_e32 v34, v32, v207
	v_mul_f32_e32 v35, v32, v208
	v_exp_f32_e32 v34, v34
	v_exp_f32_e32 v35, v35
	v_mul_f32_e32 v38, v32, v209
	v_mul_f32_e32 v39, v32, v210
	v_cndmask_b32_e64 v37, v33, 0, s[10:11]
	v_lshrrev_b32_e32 v33, 16, v33
	v_exp_f32_e32 v38, v38
	v_exp_f32_e32 v39, v39
	v_cndmask_b32_e64 v33, v33, 0, s[8:9]
	v_pk_mul_f32 v[34:35], v[88:89], v[34:35]
	v_perm_b32 v37, v33, v37, s93
	v_cvt_pk_bf16_f32 v33, v34, v35
	v_cndmask_b32_e64 v34, v33, 0, s[14:15]
	v_lshrrev_b32_e32 v33, 16, v33
	v_pk_mul_f32 v[38:39], v[90:91], v[38:39]
	v_cndmask_b32_e64 v33, v33, 0, s[12:13]
	v_perm_b32 v34, v33, v34, s93
	v_cvt_pk_bf16_f32 v33, v38, v39
	v_cndmask_b32_e64 v35, v33, 0, s[18:19]
	v_lshrrev_b32_e32 v33, 16, v33
	v_cndmask_b32_e64 v33, v33, 0, s[16:17]
	v_perm_b32 v35, v33, v35, s93
	v_mul_f32_e32 v33, v32, v211
	v_exp_f32_e32 v38, v33
	v_mul_f32_e32 v33, v32, v212
	v_exp_f32_e32 v39, v33
	v_mul_f32_e32 v33, v32, v213
	v_exp_f32_e32 v40, v33
	v_mul_f32_e32 v33, v32, v214
	v_exp_f32_e32 v41, v33
	v_add_u32_e32 v33, 0x8800, v238
	ds_write2_b64 v33, v[36:37], v[34:35] offset1:4
	v_pk_mul_f32 v[34:35], v[84:85], v[38:39]
	v_pk_mul_f32 v[36:37], v[86:87], v[40:41]
	v_cvt_pk_bf16_f32 v34, v34, v35
	v_cndmask_b32_e64 v35, v34, 0, s[22:23]
	v_lshrrev_b32_e32 v34, 16, v34
	v_cndmask_b32_e64 v34, v34, 0, s[20:21]
	v_perm_b32 v34, v34, v35, s93
	v_cvt_pk_bf16_f32 v35, v36, v37
	v_mul_f32_e32 v36, v32, v215
	v_mul_f32_e32 v37, v32, v216
	v_exp_f32_e32 v36, v36
	v_exp_f32_e32 v37, v37
	v_mul_f32_e32 v38, v32, v217
	v_mul_f32_e32 v39, v32, v218
	v_exp_f32_e32 v38, v38
	v_exp_f32_e32 v39, v39
	v_pk_mul_f32 v[36:37], v[80:81], v[36:37]
	v_cndmask_b32_e64 v40, v35, 0, s[26:27]
	v_cvt_pk_bf16_f32 v36, v36, v37
	v_cndmask_b32_e64 v37, v36, 0, s[30:31]
	v_lshrrev_b32_e32 v36, 16, v36
	v_pk_mul_f32 v[38:39], v[82:83], v[38:39]
	v_cndmask_b32_e64 v36, v36, 0, s[28:29]
	v_perm_b32 v36, v36, v37, s93
	v_cvt_pk_bf16_f32 v37, v38, v39
	v_mul_f32_e32 v38, v32, v219
	v_mul_f32_e32 v39, v32, v222
	v_lshrrev_b32_e32 v35, 16, v35
	v_exp_f32_e32 v38, v38
	v_exp_f32_e32 v39, v39
	v_cndmask_b32_e64 v35, v35, 0, s[24:25]
	v_cndmask_b32_e64 v42, v37, 0, s[36:37]
	v_lshrrev_b32_e32 v37, 16, v37
	v_perm_b32 v35, v35, v40, s93
	v_cndmask_b32_e64 v37, v37, 0, s[34:35]
	v_mul_f32_e32 v40, v32, v223
	v_mul_f32_e32 v41, v32, v224
	v_exp_f32_e32 v40, v40
	v_exp_f32_e32 v41, v41
	v_perm_b32 v37, v37, v42, s93
	ds_write2_b64 v33, v[34:35], v[36:37] offset0:8 offset1:12
	v_pk_mul_f32 v[34:35], v[76:77], v[38:39]
	v_pk_mul_f32 v[36:37], v[78:79], v[40:41]
	v_cvt_pk_bf16_f32 v34, v34, v35
	v_cndmask_b32_e64 v35, v34, 0, s[40:41]
	v_lshrrev_b32_e32 v34, 16, v34
	v_cndmask_b32_e64 v34, v34, 0, s[38:39]
	v_perm_b32 v34, v34, v35, s93
	v_cvt_pk_bf16_f32 v35, v36, v37
	v_mul_f32_e32 v36, v32, v225
	v_mul_f32_e32 v37, v32, v226
	v_exp_f32_e32 v36, v36
	v_exp_f32_e32 v37, v37
	v_mul_f32_e32 v38, v32, v227
	v_mul_f32_e32 v39, v32, v228
	v_exp_f32_e32 v38, v38
	v_exp_f32_e32 v39, v39
	v_pk_mul_f32 v[36:37], v[72:73], v[36:37]
	v_cndmask_b32_e64 v40, v35, 0, s[44:45]
	v_cvt_pk_bf16_f32 v36, v36, v37
	v_cndmask_b32_e64 v37, v36, 0, s[48:49]
	v_lshrrev_b32_e32 v36, 16, v36
	v_pk_mul_f32 v[38:39], v[74:75], v[38:39]
	v_cndmask_b32_e64 v36, v36, 0, s[46:47]
	v_perm_b32 v36, v36, v37, s93
	v_cvt_pk_bf16_f32 v37, v38, v39
	v_mul_f32_e32 v38, v32, v229
	v_mul_f32_e32 v39, v32, v230
	v_lshrrev_b32_e32 v35, 16, v35
	v_exp_f32_e32 v38, v38
	v_exp_f32_e32 v39, v39
	v_cndmask_b32_e64 v35, v35, 0, s[42:43]
	v_cndmask_b32_e64 v42, v37, 0, s[52:53]
	v_lshrrev_b32_e32 v37, 16, v37
	v_perm_b32 v35, v35, v40, s93
	v_cndmask_b32_e64 v37, v37, 0, s[50:51]
	v_mul_f32_e32 v40, v32, v231
	v_mul_f32_e32 v41, v32, v232
	v_exp_f32_e32 v40, v40
	v_exp_f32_e32 v41, v41
	v_perm_b32 v37, v37, v42, s93
	ds_write2_b64 v33, v[34:35], v[36:37] offset0:16 offset1:20
	v_pk_mul_f32 v[34:35], v[68:69], v[38:39]
	v_pk_mul_f32 v[36:37], v[70:71], v[40:41]
	v_cvt_pk_bf16_f32 v34, v34, v35
	v_cndmask_b32_e64 v35, v34, 0, s[56:57]
	v_lshrrev_b32_e32 v34, 16, v34
	v_cndmask_b32_e64 v34, v34, 0, s[54:55]
	v_perm_b32 v34, v34, v35, s93
	v_cvt_pk_bf16_f32 v35, v36, v37
	v_mul_f32_e32 v36, v32, v233
	v_mul_f32_e32 v37, v32, v234
	v_exp_f32_e32 v36, v36
	v_exp_f32_e32 v37, v37
	v_mul_f32_e32 v38, v32, v235
	v_mul_f32_e32 v39, v32, v236
	v_exp_f32_e32 v38, v38
	v_exp_f32_e32 v39, v39
	v_pk_mul_f32 v[36:37], v[64:65], v[36:37]
	v_cndmask_b32_e64 v40, v35, 0, s[60:61]
	v_cvt_pk_bf16_f32 v36, v36, v37
	v_cndmask_b32_e64 v37, v36, 0, s[64:65]
	v_lshrrev_b32_e32 v36, 16, v36
	v_pk_mul_f32 v[38:39], v[66:67], v[38:39]
	v_cndmask_b32_e64 v36, v36, 0, s[62:63]
	v_perm_b32 v36, v36, v37, s93
	v_cvt_pk_bf16_f32 v37, v38, v39
	v_lshrrev_b32_e32 v35, 16, v35
	v_cndmask_b32_e64 v38, v37, 0, s[68:69]
	v_lshrrev_b32_e32 v37, 16, v37
	v_cndmask_b32_e64 v35, v35, 0, s[58:59]
	v_cndmask_b32_e64 v37, v37, 0, s[66:67]
	v_perm_b32 v35, v35, v40, s93
	v_perm_b32 v37, v37, v38, s93
	ds_write2_b64 v33, v[34:35], v[36:37] offset0:24 offset1:28
	s_waitcnt lgkmcnt(0)
	ds_read_b128 v[34:37], v100 offset:34816
	ds_read_b64_tr_b16 v[66:67], v197
	ds_read_b64_tr_b16 v[68:69], v197 offset:1088
	ds_read_b64_tr_b16 v[62:63], v197 offset:32
	ds_read_b64_tr_b16 v[64:65], v197 offset:1120
	ds_read_b64_tr_b16 v[58:59], v197 offset:64
	ds_read_b64_tr_b16 v[60:61], v197 offset:1152
	ds_read_b64_tr_b16 v[54:55], v197 offset:96
	ds_read_b64_tr_b16 v[56:57], v197 offset:1184
	ds_read_b64_tr_b16 v[50:51], v197 offset:128
	ds_read_b64_tr_b16 v[52:53], v197 offset:1216
	ds_read_b64_tr_b16 v[46:47], v197 offset:160
	ds_read_b64_tr_b16 v[48:49], v197 offset:1248
	ds_read_b64_tr_b16 v[42:43], v197 offset:192
	ds_read_b64_tr_b16 v[44:45], v197 offset:1280
	ds_read_b64_tr_b16 v[38:39], v197 offset:224
	ds_read_b64_tr_b16 v[40:41], v197 offset:1312
	s_waitcnt lgkmcnt(0)
	v_add_u32_e32 v33, v201, v192
	s_waitcnt lgkmcnt(0)
	v_mfma_f32_16x16x32_bf16 v[66:69], v[66:69], v[34:37], 0
	s_lshl_b32 s86, s75, 1
	v_mov_b32_e32 v153, v131
	v_mov_b32_e32 v155, v131
	v_mfma_f32_16x16x32_bf16 v[62:65], v[62:65], v[34:37], 0
	v_mov_b32_e32 v157, v131
	v_mov_b32_e32 v159, v131
	v_mov_b32_e32 v161, v131
	v_mfma_f32_16x16x32_bf16 v[58:61], v[58:61], v[34:37], 0
	v_mov_b32_e32 v163, v131
	v_mov_b32_e32 v165, v131
	v_mov_b32_e32 v167, v131
	v_mfma_f32_16x16x32_bf16 v[54:57], v[54:57], v[34:37], 0
	s_add_i32 s71, s71, s78
	s_add_i32 s79, s79, s33
	v_lshl_add_u64 v[138:139], v[138:139], 0, s[80:81]
	v_mfma_f32_16x16x32_bf16 v[50:53], v[50:53], v[34:37], 0
	v_lshl_add_u64 v[140:141], v[140:141], 0, s[80:81]
	v_lshl_add_u64 v[142:143], v[142:143], 0, s[80:81]
	s_add_i32 s3, s3, s70
	v_mfma_f32_16x16x32_bf16 v[46:49], v[46:49], v[34:37], 0
	v_mfma_f32_16x16x32_bf16 v[42:45], v[42:45], v[34:37], 0
	v_mfma_f32_16x16x32_bf16 v[34:37], v[38:41], v[34:37], 0
	ds_read_b128 v[38:41], v100 offset:34880
	ds_read_b64_tr_b16 v[102:103], v198
	ds_read_b64_tr_b16 v[104:105], v198 offset:1088
	ds_read_b64_tr_b16 v[94:95], v198 offset:32
	ds_read_b64_tr_b16 v[96:97], v198 offset:1120
	ds_read_b64_tr_b16 v[90:91], v198 offset:64
	ds_read_b64_tr_b16 v[92:93], v198 offset:1152
	ds_read_b64_tr_b16 v[86:87], v198 offset:96
	ds_read_b64_tr_b16 v[88:89], v198 offset:1184
	ds_read_b64_tr_b16 v[82:83], v198 offset:128
	ds_read_b64_tr_b16 v[84:85], v198 offset:1216
	ds_read_b64_tr_b16 v[78:79], v198 offset:160
	ds_read_b64_tr_b16 v[80:81], v198 offset:1248
	ds_read_b64_tr_b16 v[74:75], v198 offset:192
	ds_read_b64_tr_b16 v[76:77], v198 offset:1280
	ds_read_b64_tr_b16 v[70:71], v198 offset:224
	ds_read_b64_tr_b16 v[72:73], v198 offset:1312
	s_waitcnt lgkmcnt(0)
	s_waitcnt lgkmcnt(0)
	v_mfma_f32_16x16x32_bf16 v[66:69], v[102:105], v[38:41], v[66:69]
	v_mfma_f32_16x16x32_bf16 v[62:65], v[94:97], v[38:41], v[62:65]
	v_mfma_f32_16x16x32_bf16 v[58:61], v[90:93], v[38:41], v[58:61]
	v_mfma_f32_16x16x32_bf16 v[54:57], v[86:89], v[38:41], v[54:57]
	v_mfma_f32_16x16x32_bf16 v[50:53], v[82:85], v[38:41], v[50:53]
	v_mfma_f32_16x16x32_bf16 v[46:49], v[78:81], v[38:41], v[46:49]
	v_mfma_f32_16x16x32_bf16 v[42:45], v[74:77], v[38:41], v[42:45]
	v_mfma_f32_16x16x32_bf16 v[34:37], v[70:73], v[38:41], v[34:37]
	ds_read_b128 v[38:41], v100 offset:34944
	ds_read_b64_tr_b16 v[102:103], v199
	ds_read_b64_tr_b16 v[104:105], v199 offset:1088
	ds_read_b64_tr_b16 v[94:95], v199 offset:32
	ds_read_b64_tr_b16 v[96:97], v199 offset:1120
	ds_read_b64_tr_b16 v[90:91], v199 offset:64
	ds_read_b64_tr_b16 v[92:93], v199 offset:1152
	ds_read_b64_tr_b16 v[86:87], v199 offset:96
	ds_read_b64_tr_b16 v[88:89], v199 offset:1184
	ds_read_b64_tr_b16 v[82:83], v199 offset:128
	ds_read_b64_tr_b16 v[84:85], v199 offset:1216
	ds_read_b64_tr_b16 v[78:79], v199 offset:160
	ds_read_b64_tr_b16 v[80:81], v199 offset:1248
	ds_read_b64_tr_b16 v[74:75], v199 offset:192
	ds_read_b64_tr_b16 v[76:77], v199 offset:1280
	ds_read_b64_tr_b16 v[70:71], v199 offset:224
	ds_read_b64_tr_b16 v[72:73], v199 offset:1312
	s_waitcnt lgkmcnt(0)
	s_waitcnt lgkmcnt(0)
	v_mfma_f32_16x16x32_bf16 v[66:69], v[102:105], v[38:41], v[66:69]
	v_mfma_f32_16x16x32_bf16 v[62:65], v[94:97], v[38:41], v[62:65]
	v_mfma_f32_16x16x32_bf16 v[58:61], v[90:93], v[38:41], v[58:61]
	v_mfma_f32_16x16x32_bf16 v[54:57], v[86:89], v[38:41], v[54:57]
	v_mfma_f32_16x16x32_bf16 v[50:53], v[82:85], v[38:41], v[50:53]
	v_mfma_f32_16x16x32_bf16 v[46:49], v[78:81], v[38:41], v[46:49]
	v_mfma_f32_16x16x32_bf16 v[42:45], v[74:77], v[38:41], v[42:45]
	v_mfma_f32_16x16x32_bf16 v[34:37], v[70:73], v[38:41], v[34:37]
	ds_read_b128 v[38:41], v100 offset:35008
	ds_read_b64_tr_b16 v[102:103], v200
	ds_read_b64_tr_b16 v[104:105], v200 offset:1088
	ds_read_b64_tr_b16 v[96:97], v200 offset:32
	ds_read_b64_tr_b16 v[98:99], v200 offset:1120
	ds_read_b64_tr_b16 v[92:93], v200 offset:64
	ds_read_b64_tr_b16 v[94:95], v200 offset:1152
	ds_read_b64_tr_b16 v[88:89], v200 offset:96
	ds_read_b64_tr_b16 v[90:91], v200 offset:1184
	ds_read_b64_tr_b16 v[84:85], v200 offset:128
	ds_read_b64_tr_b16 v[86:87], v200 offset:1216
	ds_read_b64_tr_b16 v[76:77], v200 offset:160
	ds_read_b64_tr_b16 v[78:79], v200 offset:1248
	ds_read_b64_tr_b16 v[80:81], v200 offset:192
	ds_read_b64_tr_b16 v[82:83], v200 offset:1280
	ds_read_b64_tr_b16 v[72:73], v200 offset:224
	ds_read_b64_tr_b16 v[74:75], v200 offset:1312
	s_waitcnt lgkmcnt(0)
	s_waitcnt lgkmcnt(0)
	v_mfma_f32_16x16x32_bf16 v[116:119], v[102:105], v[38:41], v[66:69]
	v_mfma_f32_16x16x32_bf16 v[68:71], v[80:83], v[38:41], v[42:45]
	s_nop 2
	ds_read_b128 v[42:45], v33
	v_mfma_f32_16x16x32_bf16 v[112:115], v[96:99], v[38:41], v[62:65]
	s_nop 2
	v_add_u32_e32 v62, v201, v193
	v_mfma_f32_16x16x32_bf16 v[104:107], v[92:95], v[38:41], v[58:61]
	v_add_u32_e32 v63, v201, v194
	v_mfma_f32_16x16x32_bf16 v[96:99], v[88:91], v[38:41], v[54:57]
	v_mfma_f32_16x16x32_bf16 v[88:91], v[84:87], v[38:41], v[50:53]
	v_mfma_f32_16x16x32_bf16 v[76:79], v[76:79], v[38:41], v[46:49]
	v_mfma_f32_16x16x32_bf16 v[64:67], v[72:75], v[38:41], v[34:37]
	s_nop 2
	ds_read_b128 v[34:37], v100
	ds_read_b128 v[38:41], v100 offset:64
	ds_read_b128 v[46:49], v33 offset:64
	ds_read_b128 v[50:53], v33 offset:4352
	ds_read_b128 v[54:57], v33 offset:4416
	ds_read_b128 v[58:61], v33 offset:8704
	ds_read_b128 v[72:75], v33 offset:8768
	ds_read_b128 v[80:83], v62
	ds_read_b128 v[84:87], v62 offset:64
	ds_read_b128 v[92:95], v33 offset:17408
	ds_read_b128 v[108:111], v33 offset:17472
	ds_read_b128 v[120:123], v33 offset:21760
	ds_read_b128 v[124:127], v33 offset:21824
	ds_read_b128 v[168:171], v33 offset:26112
	ds_read_b128 v[172:175], v33 offset:26176
	s_waitcnt lgkmcnt(14)
	v_mfma_f32_16x16x32_bf16 v[42:45], v[42:45], v[34:37], 0
	ds_read_b128 v[176:179], v63
	ds_read_b128 v[180:183], v63 offset:64
	s_waitcnt lgkmcnt(13)
	v_mfma_f32_16x16x32_bf16 v[50:53], v[50:53], v[34:37], 0
	s_waitcnt lgkmcnt(9)
	v_mfma_f32_16x16x32_bf16 v[80:83], v[80:83], v[34:37], 0
	v_mfma_f32_16x16x32_bf16 v[42:45], v[46:49], v[38:41], v[42:45]
	v_mfma_f32_16x16x32_bf16 v[46:49], v[54:57], v[38:41], v[50:53]
	s_waitcnt lgkmcnt(8)
	v_mfma_f32_16x16x32_bf16 v[54:57], v[84:87], v[38:41], v[80:83]
	ds_read_b128 v[84:87], v33 offset:128
	v_mfma_f32_16x16x32_bf16 v[58:61], v[58:61], v[34:37], 0
	s_waitcnt lgkmcnt(8)
	v_mfma_f32_16x16x32_bf16 v[92:95], v[92:95], v[34:37], 0
	s_waitcnt lgkmcnt(6)
	v_mfma_f32_16x16x32_bf16 v[120:123], v[120:123], v[34:37], 0
	s_waitcnt lgkmcnt(4)
	v_mfma_f32_16x16x32_bf16 v[168:171], v[168:171], v[34:37], 0
	s_waitcnt lgkmcnt(2)
	v_mfma_f32_16x16x32_bf16 v[34:37], v[176:179], v[34:37], 0
	v_mfma_f32_16x16x32_bf16 v[50:53], v[72:75], v[38:41], v[58:61]
	v_mfma_f32_16x16x32_bf16 v[58:61], v[108:111], v[38:41], v[92:95]
	v_mfma_f32_16x16x32_bf16 v[72:75], v[124:127], v[38:41], v[120:123]
	v_mfma_f32_16x16x32_bf16 v[80:83], v[172:175], v[38:41], v[168:171]
	s_waitcnt lgkmcnt(1)
	v_mfma_f32_16x16x32_bf16 v[34:37], v[180:183], v[38:41], v[34:37]
	ds_read_b128 v[38:41], v100 offset:128
	ds_read_b128 v[168:171], v100 offset:192
	ds_read_b128 v[92:95], v33 offset:192
	s_waitcnt lgkmcnt(2)
	v_mfma_f32_16x16x32_bf16 v[42:45], v[84:87], v[38:41], v[42:45]
	ds_read_b128 v[84:87], v33 offset:4480
	ds_read_b128 v[100:103], v33 offset:4544
	s_waitcnt lgkmcnt(1)
	v_mfma_f32_16x16x32_bf16 v[46:49], v[84:87], v[38:41], v[46:49]
	ds_read_b128 v[84:87], v33 offset:8832
	ds_read_b128 v[108:111], v33 offset:8896
	s_waitcnt lgkmcnt(1)
	v_mfma_f32_16x16x32_bf16 v[50:53], v[84:87], v[38:41], v[50:53]
	ds_read_b128 v[84:87], v62 offset:128
	ds_read_b128 v[172:175], v62 offset:192
	s_waitcnt lgkmcnt(1)
	v_mfma_f32_16x16x32_bf16 v[54:57], v[84:87], v[38:41], v[54:57]
	ds_read_b128 v[84:87], v33 offset:17536
	ds_read_b128 v[176:179], v33 offset:17600
	s_waitcnt lgkmcnt(1)
	v_mfma_f32_16x16x32_bf16 v[58:61], v[84:87], v[38:41], v[58:61]
	ds_read_b128 v[84:87], v33 offset:21888
	ds_read_b128 v[180:183], v33 offset:21952
	s_waitcnt lgkmcnt(1)
	v_mfma_f32_16x16x32_bf16 v[72:75], v[84:87], v[38:41], v[72:75]
	ds_read_b128 v[84:87], v33 offset:26240
	ds_read_b128 v[244:247], v33 offset:26304
	v_mul_f32_e32 v33, v32, v202
	v_cmp_gt_f32_e32 vcc, s92, v33
	s_waitcnt lgkmcnt(1)
	v_mfma_f32_16x16x32_bf16 v[80:83], v[84:87], v[38:41], v[80:83]
	ds_read_b128 v[84:87], v63 offset:128
	ds_read_b128 v[248:251], v63 offset:192
	v_cndmask_b32_e32 v33, 0, v243, vcc
	s_waitcnt lgkmcnt(1)
	v_mfma_f32_16x16x32_bf16 v[34:37], v[84:87], v[38:41], v[34:37]
	v_lshlrev_b64 v[38:39], 10, v[252:253]
	v_lshl_add_u64 v[38:39], s[0:1], 0, v[38:39]
	v_lshl_add_u64 v[38:39], v[38:39], 0, s[86:87]
	v_lshl_add_u64 v[38:39], v[38:39], 0, v[152:153]
	v_mfma_f32_16x16x32_bf16 v[120:123], v[100:103], v[168:171], v[46:49]
	v_cndmask_b32_e32 v40, 0, v241, vcc
	v_fmac_f32_e32 v40, v32, v202
	v_exp_f32_e32 v32, v40
	v_mfma_f32_16x16x32_bf16 v[100:103], v[172:175], v[168:171], v[54:57]
	global_load_dwordx2 v[172:173], v[38:39], off nt
	global_load_dwordx2 v[174:175], v[38:39], off offset:32 nt
	v_ldexp_f32 v130, v32, v33
	v_and_b32_e32 v33, 64, v239
	v_xor_b32_e32 v32, 16, v239
	v_add_u32_e32 v33, 64, v33
	v_cmp_lt_i32_e32 vcc, v32, v33
	s_lshl_b32 s0, s75, 2
	s_mov_b32 s1, s87
	v_cndmask_b32_e32 v32, v239, v32, vcc
	v_lshlrev_b32_e32 v147, 2, v32
	v_xor_b32_e32 v32, 32, v239
	v_cmp_lt_i32_e32 vcc, v32, v33
	v_mfma_f32_16x16x32_bf16 v[124:127], v[92:95], v[168:171], v[42:45]
	v_fma_f32 v112, v130, v120, v112
	v_fma_f32 v113, v130, v121, v113
	v_cndmask_b32_e32 v32, v239, v32, vcc
	v_lshlrev_b32_e32 v145, 2, v32
	v_lshl_add_u64 v[32:33], v[134:135], 0, s[0:1]
	v_mfma_f32_16x16x32_bf16 v[108:111], v[108:111], v[168:171], v[50:53]
	s_nop 1
	v_fma_f32 v118, v130, v126, v118
	v_fma_f32 v119, v130, v127, v119
	v_pk_mul_f32 v[126:127], v[118:119], v[118:119]
	v_pk_fma_f32 v[124:125], v[130:131], v[124:125], v[116:117] op_sel_hi:[0,1,1]
	v_mfma_f32_16x16x32_bf16 v[92:95], v[176:179], v[168:171], v[58:61]
	v_mul_f32_e64 v120, v112, v112
	v_mul_f32_e64 v121, v113, v113
	v_pk_fma_f32 v[114:115], v[130:131], v[122:123], v[114:115] op_sel_hi:[0,1,1]
	v_pk_mul_f32 v[122:123], v[114:115], v[114:115]
	v_mfma_f32_16x16x32_bf16 v[84:87], v[180:183], v[168:171], v[72:75]
	v_fma_f32 v104, v130, v108, v104
	v_fma_f32 v105, v130, v109, v105
	v_pk_mul_f32 v[108:109], v[104:105], v[104:105]
	v_pk_fma_f32 v[106:107], v[130:131], v[110:111], v[106:107] op_sel_hi:[0,1,1]
	v_mfma_f32_16x16x32_bf16 v[72:75], v[244:247], v[168:171], v[80:83]
	v_mul_f32_e64 v110, v106, v106
	v_mul_f32_e64 v111, v107, v107
	v_pk_fma_f32 v[96:97], v[130:131], v[100:101], v[96:97] op_sel_hi:[0,1,1]
	v_pk_mul_f32 v[100:101], v[96:97], v[96:97]
	s_waitcnt lgkmcnt(0)
	v_mfma_f32_16x16x32_bf16 v[80:83], v[248:251], v[168:171], v[34:37]
	global_load_dwordx4 v[60:63], v[32:33], off
	global_load_dwordx4 v[56:59], v[32:33], off offset:64
	global_load_dwordx2 v[176:177], v[38:39], off offset:64 nt
	global_load_dwordx2 v[180:181], v[38:39], off offset:96 nt
	global_load_dwordx4 v[52:55], v[32:33], off offset:128
	global_load_dwordx4 v[48:51], v[32:33], off offset:192
	global_load_dwordx4 v[44:47], v[32:33], off offset:256
	global_load_dwordx4 v[40:43], v[32:33], off offset:320
	global_load_dwordx2 v[184:185], v[38:39], off offset:128 nt
	global_load_dwordx2 v[182:183], v[38:39], off offset:160 nt
	global_load_dwordx2 v[178:179], v[38:39], off offset:192 nt
	global_load_dwordx2 v[170:171], v[38:39], off offset:224 nt
	s_nop 0
	global_load_dwordx4 v[36:39], v[32:33], off offset:384
	s_nop 0
	global_load_dwordx4 v[32:35], v[32:33], off offset:448
	v_pk_mul_f32 v[250:251], v[124:125], v[124:125]
	v_add_f32_e32 v249, 0, v124
	v_mov_b32_e32 v248, v251
	v_mov_b32_e32 v251, v125
	v_pk_fma_f32 v[98:99], v[130:131], v[102:103], v[98:99] op_sel_hi:[0,1,1]
	v_pk_mul_f32 v[102:103], v[98:99], v[98:99]
	v_pk_fma_f32 v[88:89], v[130:131], v[92:93], v[88:89] op_sel_hi:[0,1,1]
	v_pk_mul_f32 v[92:93], v[88:89], v[88:89]
	v_pk_fma_f32 v[90:91], v[130:131], v[94:95], v[90:91] op_sel_hi:[0,1,1]
	v_pk_mul_f32 v[94:95], v[90:91], v[90:91]
	v_pk_fma_f32 v[76:77], v[130:131], v[84:85], v[76:77] op_sel_hi:[0,1,1]
	v_pk_mul_f32 v[84:85], v[76:77], v[76:77]
	v_pk_fma_f32 v[78:79], v[130:131], v[86:87], v[78:79] op_sel_hi:[0,1,1]
	v_pk_mul_f32 v[86:87], v[78:79], v[78:79]
	v_pk_fma_f32 v[68:69], v[130:131], v[72:73], v[68:69] op_sel_hi:[0,1,1]
	v_pk_mul_f32 v[72:73], v[68:69], v[68:69]
	v_pk_fma_f32 v[70:71], v[130:131], v[74:75], v[70:71] op_sel_hi:[0,1,1]
	v_pk_mul_f32 v[74:75], v[70:71], v[70:71]
	v_pk_fma_f32 v[64:65], v[130:131], v[80:81], v[64:65] op_sel_hi:[0,1,1]
	v_pk_mul_f32 v[80:81], v[64:65], v[64:65]
	v_pk_fma_f32 v[66:67], v[130:131], v[82:83], v[66:67] op_sel_hi:[0,1,1]
	v_pk_mul_f32 v[82:83], v[66:67], v[66:67]
	s_brev_b32 s0, 60
	v_lshlrev_b64 v[168:169], 11, v[252:253]
	v_lshl_add_u64 v[168:169], s[82:83], 0, v[168:169]
	v_lshl_add_u64 v[168:169], v[168:169], 0, s[86:87]
	s_waitcnt vmcnt(15)
	v_lshlrev_b32_e32 v246, 16, v172
	v_and_b32_e32 v247, 0xffff0000, v172
	v_mul_f32_e32 v149, 0xbfb8aa3b, v246
	v_exp_f32_e32 v149, v149
	v_mul_f32_e32 v151, 0xbfb8aa3b, v247
	v_exp_f32_e32 v151, v151
	v_lshlrev_b32_e32 v244, 16, v173
	v_add_f32_e32 v149, 1.0, v149
	v_rcp_f32_e32 v172, v149
	v_add_f32_e32 v149, 1.0, v151
	v_and_b32_e32 v245, 0xffff0000, v173
	v_rcp_f32_e32 v173, v149
	v_mul_f32_e32 v149, 0xbfb8aa3b, v245
	v_exp_f32_e32 v149, v149
	v_pk_mul_f32 v[116:117], v[172:173], v[246:247]
	v_mov_b32_e32 v246, v126
	v_mul_f32_e32 v126, 0xbfb8aa3b, v244
	v_exp_f32_e32 v126, v126
	v_pk_add_f32 v[172:173], v[248:249], v[250:251]
	v_mov_b32_e32 v247, v118
	v_pk_add_f32 v[172:173], v[172:173], v[246:247]
	v_add_f32_e32 v126, 1.0, v126
	v_rcp_f32_e32 v246, v126
	v_add_f32_e32 v126, 1.0, v149
	v_rcp_f32_e32 v247, v126
	v_mov_b32_e32 v126, v127
	v_mov_b32_e32 v127, v119
	v_pk_add_f32 v[248:249], v[172:173], v[126:127]
	v_mov_b32_e32 v250, v120
	v_mov_b32_e32 v251, v112
	v_pk_add_f32 v[248:249], v[248:249], v[250:251]
	s_waitcnt vmcnt(14)
	v_lshlrev_b32_e32 v250, 16, v174
	v_and_b32_e32 v251, 0xffff0000, v174
	v_mul_f32_e32 v149, 0xbfb8aa3b, v250
	v_mul_f32_e32 v151, 0xbfb8aa3b, v251
	v_exp_f32_e32 v149, v149
	v_exp_f32_e32 v151, v151
	v_pk_mul_f32 v[172:173], v[246:247], v[244:245]
	v_lshlrev_b32_e32 v246, 16, v175
	v_mov_b32_e32 v120, v121
	v_mov_b32_e32 v121, v113
	v_and_b32_e32 v247, 0xffff0000, v175
	v_pk_add_f32 v[174:175], v[248:249], v[120:121]
	v_add_f32_e32 v120, 1.0, v149
	v_add_f32_e32 v121, 1.0, v151
	v_mul_f32_e32 v149, 0xbfb8aa3b, v246
	v_rcp_f32_e32 v120, v120
	v_exp_f32_e32 v149, v149
	v_mul_f32_e32 v151, 0xbfb8aa3b, v247
	v_rcp_f32_e32 v121, v121
	v_exp_f32_e32 v151, v151
	v_mov_b32_e32 v244, v122
	v_mov_b32_e32 v245, v114
	v_mov_b32_e32 v122, v123
	v_mov_b32_e32 v123, v115
	v_pk_add_f32 v[174:175], v[174:175], v[244:245]
	v_add_f32_e32 v149, 1.0, v149
	v_pk_mul_f32 v[120:121], v[120:121], v[250:251]
	v_pk_add_f32 v[244:245], v[174:175], v[122:123]
	v_mov_b32_e32 v250, v108
	v_mov_b32_e32 v251, v104
	v_rcp_f32_e32 v248, v149
	v_add_f32_e32 v149, 1.0, v151
	v_pk_add_f32 v[244:245], v[244:245], v[250:251]
	s_waitcnt vmcnt(11)
	v_lshlrev_b32_e32 v250, 16, v176
	v_and_b32_e32 v251, 0xffff0000, v176
	v_rcp_f32_e32 v249, v149
	v_mul_f32_e32 v149, 0xbfb8aa3b, v250
	v_mul_f32_e32 v151, 0xbfb8aa3b, v251
	v_exp_f32_e32 v149, v149
	v_exp_f32_e32 v151, v151
	v_pk_mul_f32 v[174:175], v[248:249], v[246:247]
	v_lshlrev_b32_e32 v248, 16, v177
	v_mov_b32_e32 v108, v109
	v_mov_b32_e32 v109, v105
	v_and_b32_e32 v249, 0xffff0000, v177
	v_pk_add_f32 v[176:177], v[244:245], v[108:109]
	v_add_f32_e32 v108, 1.0, v149
	v_add_f32_e32 v109, 1.0, v151
	v_mul_f32_e32 v149, 0xbfb8aa3b, v248
	v_rcp_f32_e32 v108, v108
	v_exp_f32_e32 v149, v149
	v_mul_f32_e32 v151, 0xbfb8aa3b, v249
	v_rcp_f32_e32 v109, v109
	v_exp_f32_e32 v151, v151
	v_mov_b32_e32 v246, v110
	v_mov_b32_e32 v247, v106
	v_mov_b32_e32 v110, v111
	v_mov_b32_e32 v111, v107
	v_pk_add_f32 v[176:177], v[176:177], v[246:247]
	v_add_f32_e32 v149, 1.0, v149
	v_pk_mul_f32 v[108:109], v[108:109], v[250:251]
	v_pk_add_f32 v[246:247], v[176:177], v[110:111]
	v_mov_b32_e32 v250, v100
	v_mov_b32_e32 v251, v96
	v_rcp_f32_e32 v244, v149
	v_add_f32_e32 v149, 1.0, v151
	v_pk_add_f32 v[246:247], v[246:247], v[250:251]
	s_waitcnt vmcnt(10)
	v_lshlrev_b32_e32 v250, 16, v180
	v_and_b32_e32 v251, 0xffff0000, v180
	v_rcp_f32_e32 v245, v149
	v_mul_f32_e32 v149, 0xbfb8aa3b, v250
	v_mul_f32_e32 v151, 0xbfb8aa3b, v251
	v_exp_f32_e32 v149, v149
	v_exp_f32_e32 v151, v151
	v_pk_mul_f32 v[176:177], v[244:245], v[248:249]
	v_lshlrev_b32_e32 v248, 16, v181
	v_mov_b32_e32 v100, v101
	v_mov_b32_e32 v101, v97
	v_and_b32_e32 v249, 0xffff0000, v181
	v_pk_add_f32 v[180:181], v[246:247], v[100:101]
	v_add_f32_e32 v100, 1.0, v149
	v_add_f32_e32 v101, 1.0, v151
	v_mul_f32_e32 v149, 0xbfb8aa3b, v248
	v_rcp_f32_e32 v100, v100
	v_exp_f32_e32 v149, v149
	v_mul_f32_e32 v151, 0xbfb8aa3b, v249
	v_rcp_f32_e32 v101, v101
	v_exp_f32_e32 v151, v151
	v_mov_b32_e32 v244, v102
	v_mov_b32_e32 v245, v98
	v_mov_b32_e32 v102, v103
	v_mov_b32_e32 v103, v99
	v_pk_add_f32 v[180:181], v[180:181], v[244:245]
	v_add_f32_e32 v149, 1.0, v149
	v_pk_mul_f32 v[100:101], v[100:101], v[250:251]
	v_pk_add_f32 v[244:245], v[180:181], v[102:103]
	v_mov_b32_e32 v250, v92
	v_mov_b32_e32 v251, v88
	v_rcp_f32_e32 v246, v149
	v_add_f32_e32 v149, 1.0, v151
	v_pk_add_f32 v[244:245], v[244:245], v[250:251]
	s_waitcnt vmcnt(5)
	v_lshlrev_b32_e32 v250, 16, v184
	v_and_b32_e32 v251, 0xffff0000, v184
	v_rcp_f32_e32 v247, v149
	v_mul_f32_e32 v149, 0xbfb8aa3b, v250
	v_mul_f32_e32 v151, 0xbfb8aa3b, v251
	v_exp_f32_e32 v149, v149
	v_exp_f32_e32 v151, v151
	v_pk_mul_f32 v[180:181], v[246:247], v[248:249]
	v_lshlrev_b32_e32 v248, 16, v185
	v_mov_b32_e32 v92, v93
	v_mov_b32_e32 v93, v89
	v_and_b32_e32 v249, 0xffff0000, v185
	v_pk_add_f32 v[184:185], v[244:245], v[92:93]
	v_add_f32_e32 v92, 1.0, v149
	v_add_f32_e32 v93, 1.0, v151
	v_mul_f32_e32 v149, 0xbfb8aa3b, v248
	v_rcp_f32_e32 v92, v92
	v_exp_f32_e32 v149, v149
	v_mul_f32_e32 v151, 0xbfb8aa3b, v249
	v_rcp_f32_e32 v93, v93
	v_exp_f32_e32 v151, v151
	v_mov_b32_e32 v246, v94
	v_mov_b32_e32 v247, v90
	v_mov_b32_e32 v94, v95
	v_mov_b32_e32 v95, v91
	v_pk_add_f32 v[184:185], v[184:185], v[246:247]
	v_add_f32_e32 v149, 1.0, v149
	v_pk_mul_f32 v[92:93], v[92:93], v[250:251]
	v_pk_add_f32 v[246:247], v[184:185], v[94:95]
	v_mov_b32_e32 v250, v84
	v_mov_b32_e32 v251, v76
	v_rcp_f32_e32 v244, v149
	v_add_f32_e32 v149, 1.0, v151
	v_pk_add_f32 v[246:247], v[246:247], v[250:251]
	s_waitcnt vmcnt(4)
	v_lshlrev_b32_e32 v250, 16, v182
	v_and_b32_e32 v251, 0xffff0000, v182
	v_rcp_f32_e32 v245, v149
	v_mul_f32_e32 v149, 0xbfb8aa3b, v250
	v_mul_f32_e32 v151, 0xbfb8aa3b, v251
	v_exp_f32_e32 v149, v149
	v_exp_f32_e32 v151, v151
	v_pk_mul_f32 v[184:185], v[244:245], v[248:249]
	v_lshlrev_b32_e32 v248, 16, v183
	v_mov_b32_e32 v84, v85
	v_mov_b32_e32 v85, v77
	v_and_b32_e32 v249, 0xffff0000, v183
	v_pk_add_f32 v[182:183], v[246:247], v[84:85]
	v_add_f32_e32 v84, 1.0, v149
	v_add_f32_e32 v85, 1.0, v151
	v_mul_f32_e32 v149, 0xbfb8aa3b, v248
	v_rcp_f32_e32 v84, v84
	v_exp_f32_e32 v149, v149
	v_mul_f32_e32 v151, 0xbfb8aa3b, v249
	v_rcp_f32_e32 v85, v85
	v_exp_f32_e32 v151, v151
	v_mov_b32_e32 v244, v86
	v_mov_b32_e32 v245, v78
	v_mov_b32_e32 v86, v87
	v_mov_b32_e32 v87, v79
	v_pk_add_f32 v[182:183], v[182:183], v[244:245]
	v_add_f32_e32 v149, 1.0, v149
	v_pk_mul_f32 v[84:85], v[84:85], v[250:251]
	v_pk_add_f32 v[244:245], v[182:183], v[86:87]
	v_mov_b32_e32 v250, v72
	v_mov_b32_e32 v251, v68
	v_rcp_f32_e32 v246, v149
	v_add_f32_e32 v149, 1.0, v151
	v_pk_add_f32 v[244:245], v[244:245], v[250:251]
	s_waitcnt vmcnt(3)
	v_lshlrev_b32_e32 v250, 16, v178
	v_rcp_f32_e32 v247, v149
	v_and_b32_e32 v251, 0xffff0000, v178
	v_mul_f32_e32 v149, 0xbfb8aa3b, v250
	v_exp_f32_e32 v149, v149
	v_mul_f32_e32 v151, 0xbfb8aa3b, v251
	v_exp_f32_e32 v151, v151
	v_pk_mul_f32 v[182:183], v[246:247], v[248:249]
	v_lshlrev_b32_e32 v248, 16, v179
	v_mov_b32_e32 v72, v73
	v_mov_b32_e32 v73, v69
	v_and_b32_e32 v249, 0xffff0000, v179
	v_pk_add_f32 v[178:179], v[244:245], v[72:73]
	v_add_f32_e32 v72, 1.0, v149
	v_mul_f32_e32 v149, 0xbfb8aa3b, v248
	v_add_f32_e32 v73, 1.0, v151
	v_exp_f32_e32 v149, v149
	v_mul_f32_e32 v151, 0xbfb8aa3b, v249
	v_exp_f32_e32 v151, v151
	v_mov_b32_e32 v246, v74
	v_add_f32_e32 v149, 1.0, v149
	v_rcp_f32_e32 v244, v149
	v_add_f32_e32 v149, 1.0, v151
	v_mov_b32_e32 v247, v70
	v_rcp_f32_e32 v245, v149
	v_mov_b32_e32 v74, v75
	v_mov_b32_e32 v75, v71
	v_pk_add_f32 v[178:179], v[178:179], v[246:247]
	v_mov_b32_e32 v246, v80
	v_pk_add_f32 v[178:179], v[178:179], v[74:75]
	v_mov_b32_e32 v247, v64
	v_mov_b32_e32 v80, v81
	v_mov_b32_e32 v81, v65
	v_pk_add_f32 v[178:179], v[178:179], v[246:247]
	v_pk_mul_f32 v[74:75], v[244:245], v[248:249]
	v_mov_b32_e32 v244, v82
	v_mov_b32_e32 v245, v66
	v_pk_add_f32 v[80:81], v[178:179], v[80:81]
	v_mov_b32_e32 v82, v83
	v_mov_b32_e32 v83, v67
	v_pk_add_f32 v[80:81], v[80:81], v[244:245]
	s_waitcnt vmcnt(2)
	v_lshlrev_b32_e32 v178, 16, v170
	v_pk_add_f32 v[82:83], v[80:81], v[82:83]
	ds_bpermute_b32 v245, v147, v83
	ds_bpermute_b32 v244, v147, v82
	v_mul_f32_e32 v130, 0xbfb8aa3b, v178
	v_and_b32_e32 v179, 0xffff0000, v170
	v_exp_f32_e32 v130, v130
	v_lshl_add_u64 v[126:127], v[168:169], 0, v[152:153]
	s_waitcnt lgkmcnt(0)
	v_pk_add_f32 v[82:83], v[82:83], v[244:245]
	ds_bpermute_b32 v245, v145, v83
	ds_bpermute_b32 v244, v145, v82
	v_mul_f32_e32 v145, 0xbfb8aa3b, v179
	v_exp_f32_e32 v145, v145
	v_add_f32_e32 v130, 1.0, v130
	v_lshl_add_u64 v[122:123], v[168:169], 0, v[154:155]
	s_waitcnt lgkmcnt(0)
	v_pk_add_f32 v[82:83], v[82:83], v[244:245]
	v_rcp_f32_e32 v244, v130
	v_pk_mul_f32 v[82:83], v[82:83], s[0:1] op_sel_hi:[1,0]
	s_mov_b32 s0, 0xf800000
	v_fma_f32 v147, -v83, v83, v82
	v_max_f32_e32 v147, 0, v147
	v_add_f32_e32 v147, 0x358637bd, v147
	v_mul_f32_e32 v149, 0x4f800000, v147
	v_cmp_gt_f32_e32 vcc, s0, v147
	v_add_f32_e32 v130, 1.0, v145
	v_rcp_f32_e32 v245, v130
	v_cndmask_b32_e32 v147, v147, v149, vcc
	v_sqrt_f32_e32 v149, v147
	v_pk_add_f32 v[124:125], v[124:125], v[82:83] op_sel:[0,1] neg_lo:[0,1] neg_hi:[0,1]
	v_lshl_add_u64 v[110:111], v[168:169], 0, v[156:157]
	v_lshl_add_u64 v[102:103], v[168:169], 0, v[158:159]
	v_add_u32_e32 v130, -1, v149
	v_fma_f32 v145, -v130, v149, v147
	v_cmp_ge_f32_e64 s[0:1], 0, v145
	v_add_u32_e32 v145, 1, v149
	v_lshl_add_u64 v[94:95], v[168:169], 0, v[160:161]
	v_cndmask_b32_e64 v130, v149, v130, s[0:1]
	v_fma_f32 v149, -v145, v149, v147
	v_cmp_lt_f32_e64 s[0:1], 0, v149
	v_lshl_add_u64 v[86:87], v[168:169], 0, v[162:163]
	v_rcp_f32_e32 v72, v72
	v_cndmask_b32_e64 v130, v130, v145, s[0:1]
	v_mul_f32_e32 v145, 0x37800000, v130
	v_cndmask_b32_e32 v130, v130, v145, vcc
	v_cmp_class_f32_e32 vcc, v147, v240
	v_rcp_f32_e32 v73, v73
	v_lshl_add_u64 v[80:81], v[168:169], 0, v[164:165]
	v_cndmask_b32_e32 v130, v130, v147, vcc
	v_div_scale_f32 v145, s[0:1], v130, v130, 1.0
	v_rcp_f32_e32 v147, v145
	v_pk_mul_f32 v[72:73], v[72:73], v[250:251]
	v_lshlrev_b32_e32 v170, 16, v171
	v_and_b32_e32 v171, 0xffff0000, v171
	v_fma_f32 v149, -v145, v147, 1.0
	v_fmac_f32_e32 v147, v149, v147
	v_div_scale_f32 v149, vcc, 1.0, v130, 1.0
	v_mul_f32_e32 v151, v149, v147
	v_fma_f32 v153, -v145, v151, v149
	v_fmac_f32_e32 v151, v153, v147
	v_fma_f32 v145, -v145, v151, v149
	v_div_fmas_f32 v145, v145, v147, v151
	v_div_fixup_f32 v130, v145, v130, 1.0
	v_pk_mul_f32 v[124:125], v[130:131], v[124:125] op_sel_hi:[0,1]
	v_pk_mul_f32 v[60:61], v[124:125], v[60:61]
	v_pk_mul_f32 v[178:179], v[244:245], v[178:179]
	v_pk_mul_f32 v[60:61], v[60:61], v[116:117]
	v_pk_add_f32 v[116:117], v[118:119], v[82:83] op_sel:[0,1] neg_lo:[0,1] neg_hi:[0,1]
	v_cvt_pk_bf16_f32 v60, v60, v61
	v_pk_mul_f32 v[116:117], v[130:131], v[116:117] op_sel_hi:[0,1]
	v_pk_mul_f32 v[62:63], v[116:117], v[62:63]
	s_andn2_b64 vcc, exec, s[96:97]
	v_pk_mul_f32 v[62:63], v[62:63], v[172:173]
	s_nop 0
	v_cvt_pk_bf16_f32 v61, v62, v63
	global_store_dwordx2 v[126:127], v[60:61], off sc1
	v_pk_add_f32 v[60:61], v[112:113], v[82:83] op_sel:[0,1] neg_lo:[0,1] neg_hi:[0,1]
	s_nop 0
	v_pk_mul_f32 v[60:61], v[130:131], v[60:61] op_sel_hi:[0,1]
	v_pk_mul_f32 v[56:57], v[60:61], v[56:57]
	v_pk_add_f32 v[60:61], v[114:115], v[82:83] op_sel:[0,1] neg_lo:[0,1] neg_hi:[0,1]
	v_pk_mul_f32 v[56:57], v[56:57], v[120:121]
	v_pk_mul_f32 v[60:61], v[130:131], v[60:61] op_sel_hi:[0,1]
	v_pk_mul_f32 v[58:59], v[60:61], v[58:59]
	v_cvt_pk_bf16_f32 v56, v56, v57
	v_pk_mul_f32 v[58:59], v[58:59], v[174:175]
	s_nop 0
	v_cvt_pk_bf16_f32 v57, v58, v59
	global_store_dwordx2 v[122:123], v[56:57], off sc1
	v_pk_add_f32 v[56:57], v[104:105], v[82:83] op_sel:[0,1] neg_lo:[0,1] neg_hi:[0,1]
	s_nop 0
	v_pk_mul_f32 v[56:57], v[130:131], v[56:57] op_sel_hi:[0,1]
	v_pk_mul_f32 v[52:53], v[56:57], v[52:53]
	v_pk_add_f32 v[56:57], v[106:107], v[82:83] op_sel:[0,1] neg_lo:[0,1] neg_hi:[0,1]
	v_pk_mul_f32 v[52:53], v[52:53], v[108:109]
	v_pk_mul_f32 v[56:57], v[130:131], v[56:57] op_sel_hi:[0,1]
	v_pk_mul_f32 v[54:55], v[56:57], v[54:55]
	v_cvt_pk_bf16_f32 v52, v52, v53
	v_pk_mul_f32 v[54:55], v[54:55], v[176:177]
	s_nop 0
	v_cvt_pk_bf16_f32 v53, v54, v55
	global_store_dwordx2 v[110:111], v[52:53], off sc1
	v_pk_add_f32 v[52:53], v[96:97], v[82:83] op_sel:[0,1] neg_lo:[0,1] neg_hi:[0,1]
	s_nop 0
	v_pk_mul_f32 v[52:53], v[130:131], v[52:53] op_sel_hi:[0,1]
	v_pk_mul_f32 v[48:49], v[52:53], v[48:49]
	v_pk_add_f32 v[52:53], v[98:99], v[82:83] op_sel:[0,1] neg_lo:[0,1] neg_hi:[0,1]
	v_pk_mul_f32 v[48:49], v[48:49], v[100:101]
	v_pk_mul_f32 v[52:53], v[130:131], v[52:53] op_sel_hi:[0,1]
	v_pk_mul_f32 v[50:51], v[52:53], v[50:51]
	v_cvt_pk_bf16_f32 v48, v48, v49
	v_pk_mul_f32 v[50:51], v[50:51], v[180:181]
	s_nop 0
	v_cvt_pk_bf16_f32 v49, v50, v51
	global_store_dwordx2 v[102:103], v[48:49], off sc1
	v_pk_add_f32 v[48:49], v[88:89], v[82:83] op_sel:[0,1] neg_lo:[0,1] neg_hi:[0,1]
	s_nop 0
	v_pk_mul_f32 v[48:49], v[130:131], v[48:49] op_sel_hi:[0,1]
	v_pk_mul_f32 v[44:45], v[48:49], v[44:45]
	v_pk_add_f32 v[48:49], v[90:91], v[82:83] op_sel:[0,1] neg_lo:[0,1] neg_hi:[0,1]
	v_pk_mul_f32 v[44:45], v[44:45], v[92:93]
	v_pk_mul_f32 v[48:49], v[130:131], v[48:49] op_sel_hi:[0,1]
	v_pk_mul_f32 v[46:47], v[48:49], v[46:47]
	v_cvt_pk_bf16_f32 v44, v44, v45
	v_pk_mul_f32 v[46:47], v[46:47], v[184:185]
	s_nop 0
	v_cvt_pk_bf16_f32 v45, v46, v47
	global_store_dwordx2 v[94:95], v[44:45], off sc1
	v_pk_add_f32 v[44:45], v[76:77], v[82:83] op_sel:[0,1] neg_lo:[0,1] neg_hi:[0,1]
	s_nop 0
	v_pk_mul_f32 v[44:45], v[130:131], v[44:45] op_sel_hi:[0,1]
	v_pk_mul_f32 v[40:41], v[44:45], v[40:41]
	v_pk_add_f32 v[44:45], v[78:79], v[82:83] op_sel:[0,1] neg_lo:[0,1] neg_hi:[0,1]
	v_pk_mul_f32 v[40:41], v[40:41], v[84:85]
	v_pk_mul_f32 v[44:45], v[130:131], v[44:45] op_sel_hi:[0,1]
	v_pk_mul_f32 v[42:43], v[44:45], v[42:43]
	v_cvt_pk_bf16_f32 v40, v40, v41
	v_pk_mul_f32 v[42:43], v[42:43], v[182:183]
	s_nop 0
	v_cvt_pk_bf16_f32 v41, v42, v43
	global_store_dwordx2 v[86:87], v[40:41], off sc1
	v_pk_add_f32 v[40:41], v[68:69], v[82:83] op_sel:[0,1] neg_lo:[0,1] neg_hi:[0,1]
	s_nop 0
	v_pk_mul_f32 v[40:41], v[130:131], v[40:41] op_sel_hi:[0,1]
	s_waitcnt vmcnt(7)
	v_pk_mul_f32 v[36:37], v[40:41], v[36:37]
	v_pk_add_f32 v[40:41], v[70:71], v[82:83] op_sel:[0,1] neg_lo:[0,1] neg_hi:[0,1]
	v_pk_mul_f32 v[36:37], v[36:37], v[72:73]
	v_pk_mul_f32 v[40:41], v[130:131], v[40:41] op_sel_hi:[0,1]
	v_pk_mul_f32 v[38:39], v[40:41], v[38:39]
	v_cvt_pk_bf16_f32 v36, v36, v37
	v_pk_mul_f32 v[38:39], v[38:39], v[74:75]
	s_nop 0
	v_cvt_pk_bf16_f32 v37, v38, v39
	global_store_dwordx2 v[80:81], v[36:37], off sc1
	v_pk_add_f32 v[36:37], v[64:65], v[82:83] op_sel:[0,1] neg_lo:[0,1] neg_hi:[0,1]
	v_pk_add_f32 v[38:39], v[66:67], v[82:83] op_sel:[0,1] neg_lo:[0,1] neg_hi:[0,1]
	v_pk_mul_f32 v[36:37], v[130:131], v[36:37] op_sel_hi:[0,1]
	s_waitcnt vmcnt(7)
	v_pk_mul_f32 v[32:33], v[36:37], v[32:33]
	v_mul_f32_e32 v36, 0xbfb8aa3b, v170
	v_mul_f32_e32 v37, 0xbfb8aa3b, v171
	v_exp_f32_e32 v36, v36
	v_exp_f32_e32 v37, v37
	v_pk_mul_f32 v[38:39], v[130:131], v[38:39] op_sel_hi:[0,1]
	v_pk_mul_f32 v[34:35], v[38:39], v[34:35]
	v_add_f32_e32 v36, 1.0, v36
	v_add_f32_e32 v37, 1.0, v37
	v_rcp_f32_e32 v36, v36
	v_rcp_f32_e32 v37, v37
	v_pk_mul_f32 v[32:33], v[32:33], v[178:179]
	v_pk_mul_f32 v[36:37], v[36:37], v[170:171]
	s_nop 0
	v_pk_mul_f32 v[34:35], v[34:35], v[36:37]
	v_cvt_pk_bf16_f32 v32, v32, v33
	v_cvt_pk_bf16_f32 v33, v34, v35
	v_lshl_add_u64 v[34:35], v[168:169], 0, v[166:167]
	global_store_dwordx2 v[34:35], v[32:33], off sc1
	s_barrier
	s_cbranch_vccz .LBB0_580
